# attention K/V tile loads hoisted to iteration top with dedicated staging registers
# baseline (speedup 1.0000x reference)
.LBB0_691:
	v_mov_b32_e32 v0, v117
	s_and_b32 s52, s5, 3
	v_mbcnt_lo_u32_b32 v0, -1, v0
	s_add_u32 s24, s8, 0x14297900
	v_mbcnt_hi_u32_b32 v0, -1, v0
	s_addc_u32 s25, s9, 0
	v_add_u32_e32 v4, s33, v0
	s_mul_i32 s34, s50, 0x900
	s_mul_hi_i32 s35, s50, 0x900
	s_add_u32 s0, s34, s4
	v_ashrrev_i32_e32 v0, 1, v4
	v_and_b32_e32 v116, 31, v4
	s_addc_u32 s1, s35, 0
	v_and_b32_e32 v0, 0xffffffe0, v0
	v_ashrrev_i32_e32 v1, 31, v0
	v_lshl_add_u64 v[2:3], s[0:1], 0, v[116:117]
	v_lshl_add_u64 v[118:119], v[2:3], 0, v[0:1]
	v_mov_b64_e32 v[0:1], s[8:9]
	v_mad_u64_u32 v[0:1], s[0:1], v118, s54, v[0:1]
	v_bfe_u32 v5, v4, 5, 1
	v_mad_i32_i24 v1, v119, s54, v1
	s_mul_i32 s16, s52, 0xc0
	v_lshl_add_u64 v[2:3], v[0:1], 0, s[16:17]
	v_lshlrev_b32_e32 v0, 4, v5
	v_mov_b32_e32 v1, v117
	v_lshl_add_u64 v[2:3], v[2:3], 0, v[0:1]
	v_lshl_add_u64 v[6:7], v[2:3], 0, s[38:39]
	v_add_co_u32_e32 v2, vcc, s69, v2
	v_mul_hi_i32 v1, v4, s70
	s_nop 0
	v_addc_co_u32_e32 v3, vcc, 0, v3, vcc
	global_load_dwordx4 v[80:83], v[6:7], off offset:32
	global_load_dwordx4 v[76:79], v[6:7], off offset:64
	global_load_dwordx4 v[72:75], v[6:7], off offset:96
	global_load_dwordx4 v[68:71], v[6:7], off offset:128
	global_load_dwordx4 v[84:87], v[2:3], off offset:2304
	global_load_dwordx4 v[64:67], v[6:7], off offset:160
	v_lshrrev_b32_e32 v2, 31, v1
	v_ashrrev_i32_e32 v1, 1, v1
	v_add_u32_e32 v2, v1, v2
	s_add_u32 s26, s8, 0x13097900
	v_mad_u64_u32 v[8:9], s[0:1], v2, -12, v[4:5]
	v_ashrrev_i32_e32 v3, 31, v2
	s_addc_u32 s27, s9, 0
	v_cmp_gt_i32_e32 vcc, 8, v8
	v_cmp_lt_i32_e64 s[0:1], 7, v8
	v_mad_i64_i32 v[12:13], s[4:5], s50, v156, v[2:3]
	s_and_saveexec_b64 s[4:5], s[0:1]
	s_xor_b64 s[0:1], exec, s[4:5]
	v_lshlrev_b64 v[6:7], 6, v[12:13]
	v_lshl_add_u64 v[6:7], s[24:25], 0, v[6:7]
	v_lshl_add_u32 v10, v8, 3, v160
	v_mov_b32_e32 v11, v117
	v_lshl_add_u64 v[10:11], v[10:11], 1, v[6:7]
	s_or_saveexec_b64 s[0:1], s[0:1]
	v_lshlrev_b32_e32 v6, 3, v8
	v_ashrrev_i32_e32 v7, 31, v6
	s_xor_b64 exec, exec, s[0:1]
	v_lshlrev_b64 v[10:11], 9, v[12:13]
	v_lshl_add_u64 v[10:11], s[26:27], 0, v[10:11]
	s_lshl_b32 s16, s52, 7
	v_lshl_add_u64 v[10:11], v[10:11], 0, s[16:17]
	v_lshl_add_u64 v[10:11], v[6:7], 1, v[10:11]
	s_or_b64 exec, exec, s[0:1]
	global_load_dwordx4 v[224:227], v[10:11], off
	v_add_u32_e32 v16, 0x100, v4
	v_mul_hi_i32 v1, v16, s70
	v_lshrrev_b32_e32 v9, 31, v1
	v_ashrrev_i32_e32 v1, 1, v1
	v_add_u32_e32 v10, v1, v9
	v_mad_u64_u32 v[14:15], s[0:1], v10, -12, v[16:17]
	v_ashrrev_i32_e32 v11, 31, v10
	v_cmp_gt_i32_e64 s[4:5], 8, v14
	v_cmp_lt_i32_e64 s[0:1], 7, v14
	v_lshl_add_u64 v[20:21], s[34:35], 0, v[10:11]
	s_and_saveexec_b64 s[6:7], s[0:1]
	s_xor_b64 s[0:1], exec, s[6:7]
	v_lshlrev_b64 v[12:13], 6, v[20:21]
	v_lshl_add_u64 v[12:13], s[24:25], 0, v[12:13]
	v_lshl_add_u32 v18, v14, 3, v160
	v_mov_b32_e32 v19, v117
	v_lshl_add_u64 v[18:19], v[18:19], 1, v[12:13]
	s_or_saveexec_b64 s[0:1], s[0:1]
	v_lshlrev_b32_e32 v12, 3, v14
	v_ashrrev_i32_e32 v13, 31, v12
	s_xor_b64 exec, exec, s[0:1]
	v_lshlrev_b64 v[18:19], 9, v[20:21]
	v_lshl_add_u64 v[18:19], s[26:27], 0, v[18:19]
	s_lshl_b32 s16, s52, 7
	v_lshl_add_u64 v[18:19], v[18:19], 0, s[16:17]
	v_lshl_add_u64 v[18:19], v[12:13], 1, v[18:19]
	s_or_b64 exec, exec, s[0:1]
	global_load_dwordx4 v[228:231], v[18:19], off
	v_add_u32_e32 v20, 0x200, v4
	v_mul_hi_i32 v1, v20, s70
	v_lshrrev_b32_e32 v9, 31, v1
	v_ashrrev_i32_e32 v1, 1, v1
	v_add_u32_e32 v18, v1, v9
	v_mad_u64_u32 v[24:25], s[0:1], v18, -12, v[20:21]
	v_ashrrev_i32_e32 v19, 31, v18
	v_lshlrev_b32_e32 v20, 3, v24
	v_cmp_gt_i32_e64 s[6:7], 8, v24
	v_cmp_lt_i32_e64 s[0:1], 7, v24
	v_lshl_add_u64 v[28:29], s[34:35], 0, v[18:19]
	v_subrev_u32_e32 v22, 64, v20
	v_ashrrev_i32_e32 v21, 31, v20
	s_and_saveexec_b64 s[34:35], s[0:1]
	s_xor_b64 s[0:1], exec, s[34:35]
	v_lshlrev_b64 v[26:27], 6, v[28:29]
	v_lshl_add_u64 v[26:27], s[24:25], 0, v[26:27]
	v_mov_b32_e32 v23, v117
	v_lshl_add_u64 v[26:27], v[22:23], 1, v[26:27]
	s_lshl_b32 s16, s52, 6
	s_or_saveexec_b64 s[0:1], s[0:1]
	v_mov_b64_e32 v[120:121], s[16:17]
	v_mov_b32_e32 v1, s16
	s_xor_b64 exec, exec, s[0:1]
	s_cbranch_execz .LBB0_703
	v_lshlrev_b64 v[26:27], 9, v[28:29]
	v_lshl_add_u64 v[26:27], s[26:27], 0, v[26:27]
	s_lshl_b32 s24, s52, 7
	s_mov_b32 s25, s17
	s_lshl_b32 s16, s52, 6
	v_lshl_add_u64 v[26:27], v[26:27], 0, s[24:25]
	v_lshl_add_u64 v[26:27], v[20:21], 1, v[26:27]
	v_mov_b32_e32 v23, v117
	v_mov_b64_e32 v[120:121], s[16:17]
	v_mov_b32_e32 v1, s16
.LBB0_703:
	s_or_b64 exec, exec, s[0:1]
	s_add_u32 s0, s8, 0x144d7900
	s_addc_u32 s1, s9, 0
	v_ashrrev_i32_e32 v9, 3, v4
	v_lshl_add_u32 v1, s50, 8, v1
	v_lshlrev_b32_e32 v122, 3, v5
	v_add_u32_e32 v5, v1, v9
	v_mov_b64_e32 v[28:29], s[0:1]
	v_lshlrev_b32_e32 v4, 4, v4
	v_ashrrev_i32_e32 v15, 3, v16
	global_load_dwordx4 v[232:235], v[26:27], off
	v_mad_i64_i32 v[26:27], s[24:25], v5, s71, 0
	v_mad_i64_i32 v[30:31], s[0:1], v5, s71, v[28:29]
	v_and_b32_e32 v4, 0x70, v4
	v_mov_b32_e32 v5, v117
	v_add_u32_e32 v1, v1, v15
	v_lshl_add_u64 v[30:31], v[30:31], 0, v[4:5]
	v_mad_i64_i32 v[28:29], s[0:1], v1, s71, v[28:29]
	v_lshl_add_u64 v[28:29], v[28:29], 0, v[4:5]
	global_load_dwordx4 v[236:239], v[30:31], off
	global_load_dwordx4 v[240:243], v[28:29], off
	v_and_b32_e32 v5, 64, v161
	v_mad_i64_i32 v[16:17], s[0:1], v1, s71, 0
	v_xor_b32_e32 v1, 32, v161
	v_add_u32_e32 v5, 64, v5
	v_cmp_lt_i32_e64 s[0:1], v1, v5
	s_mul_i32 s16, s50, 0x24000
	v_lshlrev_b32_e32 v25, 4, v8
	v_cndmask_b32_e64 v1, v161, v1, s[0:1]
	s_add_i32 s0, s51, 1
	v_or_b32_e32 v8, 32, v116
	s_mul_hi_i32 s1, s50, 0x24000
	s_add_u32 s24, s16, 0x14298900
	v_lshlrev_b32_e32 v123, 2, v1
	v_mul_u32_u24_e32 v163, 0x90, v116
	v_mul_u32_u24_e32 v1, 0xd0, v116
	v_mul_lo_u32 v35, v9, s72
	v_mul_u32_u24_e32 v116, 0x90, v8
	s_addc_u32 s25, s1, 0
	v_lshlrev_b64 v[8:9], 6, v[18:19]
	s_mul_i32 s16, s50, 0x120000
	v_lshl_add_u64 v[8:9], s[24:25], 0, v[8:9]
	s_mul_hi_i32 s1, s50, 0x120000
	s_add_u32 s26, s16, 0x1309f900
	v_lshl_add_u64 v[128:129], v[22:23], 1, v[8:9]
	s_addc_u32 s27, s1, 0
	v_lshlrev_b64 v[8:9], 9, v[18:19]
	v_lshlrev_b32_e32 v33, 4, v14
	v_mul_lo_u32 v36, v15, s72
	v_lshl_add_u64 v[8:9], s[26:27], 0, v[8:9]
	v_lshl_add_u64 v[14:15], v[20:21], 0, v[120:121]
	v_lshl_add_u64 v[130:131], v[14:15], 1, v[8:9]
	v_lshlrev_b64 v[8:9], 6, v[10:11]
	v_subrev_u32_e32 v30, 64, v12
	v_mov_b32_e32 v31, v117
	v_lshl_add_u64 v[8:9], s[24:25], 0, v[8:9]
	v_lshl_add_u64 v[132:133], v[30:31], 1, v[8:9]
	v_lshlrev_b64 v[8:9], 9, v[10:11]
	v_mul_lo_u32 v32, v10, s73
	v_lshl_add_u64 v[8:9], s[26:27], 0, v[8:9]
	v_lshl_add_u64 v[10:11], v[120:121], 0, v[12:13]
	v_mul_lo_u32 v5, v2, s73
	v_lshl_add_u64 v[134:135], v[10:11], 1, v[8:9]
	v_lshlrev_b64 v[8:9], 6, v[2:3]
	v_lshlrev_b64 v[2:3], 9, v[2:3]
	v_subrev_u32_e32 v28, 64, v6
	v_mov_b32_e32 v29, v117
	v_mul_lo_u32 v34, v18, s73
	v_lshlrev_b32_e32 v24, 4, v24
	v_or_b32_e32 v16, v16, v4
	v_or_b32_e32 v26, v26, v4
	v_lshl_add_u64 v[8:9], s[24:25], 0, v[8:9]
	v_lshl_add_u64 v[2:3], s[26:27], 0, v[2:3]
	v_lshl_add_u64 v[6:7], v[120:121], 0, v[6:7]
	v_mov_b32_e32 v104, 0
	v_sub_u32_e32 v162, v0, v122
	v_lshl_add_u64 v[124:125], v[16:17], 0, s[40:41]
	v_lshl_add_u64 v[126:127], v[26:27], 0, s[40:41]
	v_lshl_add_u64 v[136:137], v[28:29], 1, v[8:9]
	v_lshl_add_u64 v[138:139], v[6:7], 1, v[2:3]
	v_mov_b32_e32 v105, 0xf149f2ca
	v_add_u32_e32 v165, v5, v25
	v_add_u32_e32 v166, v32, v33
	v_add_u32_e32 v167, v34, v24
	v_add_u32_e32 v168, v4, v35
	v_add_u32_e32 v169, v4, v36
	v_add_u32_e32 v164, v0, v1
	v_mov_b32_e32 v0, 0
	v_mov_b32_e32 v1, v104
	v_mov_b32_e32 v2, v104
	v_mov_b32_e32 v3, v104
	v_mov_b32_e32 v4, v104
	v_mov_b32_e32 v5, v104
	v_mov_b32_e32 v6, v104
	v_mov_b32_e32 v7, v104
	v_mov_b32_e32 v8, v104
	v_mov_b32_e32 v9, v104
	v_mov_b32_e32 v10, v104
	v_mov_b32_e32 v11, v104
	v_mov_b32_e32 v12, v104
	v_mov_b32_e32 v13, v104
	v_mov_b32_e32 v14, v104
	v_mov_b32_e32 v15, v104
	v_mov_b32_e32 v16, 0
	v_mov_b32_e32 v17, v104
	v_mov_b32_e32 v18, v104
	v_mov_b32_e32 v19, v104
	v_mov_b32_e32 v20, v104
	v_mov_b32_e32 v21, v104
	v_mov_b32_e32 v22, v104
	v_mov_b32_e32 v23, v104
	v_mov_b32_e32 v24, v104
	v_mov_b32_e32 v25, v104
	v_mov_b32_e32 v26, v104
	v_mov_b32_e32 v27, v104
	v_mov_b32_e32 v28, v104
	v_mov_b32_e32 v29, v104
	v_mov_b32_e32 v30, v104
	v_mov_b32_e32 v31, v104
.LBB0_704:
	s_waitcnt lgkmcnt(0)
	s_barrier
	s_waitcnt vmcnt(0)
	ds_write_b128 v165, v[224:227]
	ds_write_b128 v166, v[228:231]
	ds_write_b128 v167, v[232:235]
	ds_write_b128 v168, v[236:239] offset:13312
	ds_write_b128 v169, v[240:243] offset:13312
	s_waitcnt lgkmcnt(0)
	s_barrier
	ds_read_b128 v[32:35], v164
	ds_read_b128 v[88:91], v164 offset:32
	v_lshl_add_u64 v[112:113], s[8:9], 0, v[138:139]
	v_lshl_add_u64 v[148:149], s[8:9], 0, v[136:137]
	v_lshl_add_u64 v[114:115], s[8:9], 0, v[134:135]
	v_lshl_add_u64 v[142:143], s[8:9], 0, v[132:133]
	v_lshl_add_u64 v[140:141], s[8:9], 0, v[130:131]
	v_lshl_add_u64 v[144:145], s[8:9], 0, v[128:129]
	v_lshl_add_u64 v[146:147], s[8:9], 0, v[126:127]
	v_cndmask_b32_e32 v113, v149, v113, vcc
	v_cndmask_b32_e32 v112, v148, v112, vcc
	v_cndmask_b32_e64 v115, v143, v115, s[4:5]
	v_cndmask_b32_e64 v114, v142, v114, s[4:5]
	v_lshl_add_u64 v[150:151], s[8:9], 0, v[124:125]
	v_cndmask_b32_e64 v145, v145, v141, s[6:7]
	v_cndmask_b32_e64 v144, v144, v140, s[6:7]
	global_load_dwordx4 v[236:239], v[146:147], off
	global_load_dwordx4 v[240:243], v[150:151], off
	global_load_dwordx4 v[224:227], v[112:113], off
	global_load_dwordx4 v[228:231], v[114:115], off
	global_load_dwordx4 v[232:235], v[144:145], off
	s_waitcnt lgkmcnt(1)
	v_mfma_f32_32x32x16_bf16 v[32:47], v[32:35], v[84:87], 0
	ds_read_b128 v[48:51], v164 offset:6656
	ds_read_b128 v[92:95], v164 offset:6688
	v_mov_b32_e32 v171, v105
	v_mov_b32_e32 v170, v104
	s_waitcnt lgkmcnt(1)
	v_mfma_f32_32x32x16_bf16 v[48:63], v[48:51], v[84:87], 0
	v_mfma_f32_32x32x16_bf16 v[32:47], v[88:91], v[80:83], v[32:47]
	ds_read_b128 v[88:91], v164 offset:64
	v_add_u32_e32 v172, v122, v163
	v_add_u32_e32 v143, 0x3000, v172
	v_add_u32_e32 v173, v122, v116
	s_waitcnt lgkmcnt(1)
	v_mfma_f32_32x32x16_bf16 v[48:63], v[92:95], v[80:83], v[48:63]
	ds_read_b128 v[100:103], v164 offset:96
	ds_read_b128 v[92:95], v164 offset:6720
	ds_read_b128 v[96:99], v164 offset:6752
	v_add_u32_e32 v174, v162, v163
	v_add_u32_e32 v175, v162, v116
	v_add_u32_e32 v142, 0x3000, v173
	v_add_u32_e32 v141, 0x3000, v174
	v_add_u32_e32 v140, 0x3000, v175
	s_waitcnt lgkmcnt(3)
	v_mfma_f32_32x32x16_bf16 v[32:47], v[88:91], v[76:79], v[32:47]
	s_add_i32 s0, s0, -1
	v_lshl_add_u64 v[124:125], v[124:125], 0, s[42:43]
	v_lshl_add_u64 v[126:127], v[126:127], 0, s[42:43]
	v_lshl_add_u64 v[128:129], v[128:129], 0, s[44:45]
	v_lshl_add_u64 v[130:131], v[130:131], 0, s[46:47]
	v_lshl_add_u64 v[132:133], v[132:133], 0, s[44:45]
	v_lshl_add_u64 v[134:135], v[134:135], 0, s[46:47]
	s_waitcnt lgkmcnt(1)
	v_mfma_f32_32x32x16_bf16 v[48:63], v[92:95], v[76:79], v[48:63]
	ds_read_b128 v[88:91], v164 offset:128
	ds_read_b128 v[104:107], v164 offset:160
	ds_read_b128 v[92:95], v164 offset:6784
	ds_read_b128 v[108:111], v164 offset:6816
	v_lshl_add_u64 v[136:137], v[136:137], 0, s[44:45]
	v_lshl_add_u64 v[138:139], v[138:139], 0, s[46:47]
	s_cmp_lg_u32 s0, 0
	v_mfma_f32_32x32x16_bf16 v[32:47], v[100:103], v[72:75], v[32:47]
	s_waitcnt lgkmcnt(4)
	v_mfma_f32_32x32x16_bf16 v[48:63], v[96:99], v[72:75], v[48:63]
	s_waitcnt lgkmcnt(0)
	v_mfma_f32_32x32x16_bf16 v[32:47], v[88:91], v[68:71], v[32:47]
	v_mfma_f32_32x32x16_bf16 v[48:63], v[92:95], v[68:71], v[48:63]
	s_nop 0
	ds_read2_b64 v[144:147], v143 offset0:128 offset1:130
	ds_read2_b64 v[148:151], v143 offset0:132 offset1:134
	ds_read2_b64 v[172:175], v142 offset0:128 offset1:130
	ds_read2_b64 v[176:179], v142 offset0:132 offset1:134
	ds_read2_b64 v[180:183], v143 offset0:136 offset1:138
	ds_read2_b64 v[184:187], v142 offset0:136 offset1:138
	ds_read2_b64 v[188:191], v141 offset0:140 offset1:142
	ds_read2_b64 v[192:195], v140 offset0:140 offset1:142
	v_mfma_f32_32x32x16_bf16 v[32:47], v[104:107], v[64:67], v[32:47]
	v_mfma_f32_32x32x16_bf16 v[48:63], v[108:111], v[64:67], v[48:63]
	s_nop 10
	v_max_f32_e32 v104, v33, v33
	v_max_f32_e32 v105, v32, v32
	v_max_f32_e32 v104, v105, v104
	v_max3_f32 v104, v104, v34, v35
	v_max3_f32 v104, v104, v36, v37
	v_max3_f32 v104, v104, v38, v39
	v_max3_f32 v104, v104, v40, v41
	v_max3_f32 v104, v104, v42, v43
	v_max3_f32 v104, v104, v44, v45
	v_max3_f32 v104, v104, v46, v47
	v_max3_f32 v104, v104, v48, v49
	v_max3_f32 v104, v104, v50, v51
	v_max3_f32 v104, v104, v52, v53
	v_max3_f32 v104, v104, v54, v55
	v_max3_f32 v104, v104, v56, v57
	v_max3_f32 v104, v104, v58, v59
	v_max3_f32 v104, v104, v60, v61
	v_max3_f32 v104, v104, v62, v63
	ds_bpermute_b32 v105, v123, v104
	s_waitcnt lgkmcnt(0)
	v_max3_f32 v105, v171, v104, v105
	v_sub_f32_e32 v104, v171, v105
	v_sub_f32_e32 v32, v32, v105
	v_sub_f32_e32 v33, v33, v105
	v_sub_f32_e32 v34, v34, v105
	v_sub_f32_e32 v35, v35, v105
	v_sub_f32_e32 v36, v36, v105
	v_sub_f32_e32 v37, v37, v105
	v_sub_f32_e32 v38, v38, v105
	v_sub_f32_e32 v39, v39, v105
	v_sub_f32_e32 v106, v42, v105
	v_exp_f32_e32 v42, v104
	v_exp_f32_e32 v32, v32
	v_exp_f32_e32 v33, v33
	s_nop 0
	v_cvt_pk_bf16_f32 v244, v32, v33
	v_exp_f32_e32 v104, v34
	v_exp_f32_e32 v107, v35
	v_exp_f32_e32 v108, v36
	v_exp_f32_e32 v109, v37
	v_exp_f32_e32 v110, v38
	v_exp_f32_e32 v111, v39
	v_sub_f32_e32 v43, v43, v105
	v_sub_f32_e32 v40, v40, v105
	v_sub_f32_e32 v41, v41, v105
	v_exp_f32_e32 v43, v43
	v_exp_f32_e32 v171, v40
	v_exp_f32_e32 v196, v41
	v_add_f32_e32 v34, 0, v32
	v_bfe_u32 v39, v32, 16, 1
	v_add_f32_e32 v222, v33, v34
	v_add3_u32 v32, v32, v39, s59
	v_lshrrev_b32_e32 v32, 16, v32
	v_sub_f32_e32 v44, v44, v105
	v_sub_f32_e32 v45, v45, v105
	v_sub_f32_e32 v46, v46, v105
	v_pk_mul_f32 v[30:31], v[30:31], v[42:43] op_sel_hi:[1,0]
	v_pk_mul_f32 v[28:29], v[28:29], v[42:43] op_sel_hi:[1,0]
	v_pk_mul_f32 v[26:27], v[26:27], v[42:43] op_sel_hi:[1,0]
	v_pk_mul_f32 v[24:25], v[24:25], v[42:43] op_sel_hi:[1,0]
	v_pk_mul_f32 v[22:23], v[22:23], v[42:43] op_sel_hi:[1,0]
	v_pk_mul_f32 v[20:21], v[20:21], v[42:43] op_sel_hi:[1,0]
	v_pk_mul_f32 v[18:19], v[18:19], v[42:43] op_sel_hi:[1,0]
	v_pk_mul_f32 v[16:17], v[16:17], v[42:43] op_sel_hi:[1,0]
	v_pk_mul_f32 v[14:15], v[14:15], v[42:43] op_sel_hi:[1,0]
	v_pk_mul_f32 v[12:13], v[12:13], v[42:43] op_sel_hi:[1,0]
	v_pk_mul_f32 v[10:11], v[10:11], v[42:43] op_sel_hi:[1,0]
	v_pk_mul_f32 v[8:9], v[8:9], v[42:43] op_sel_hi:[1,0]
	v_pk_mul_f32 v[6:7], v[6:7], v[42:43] op_sel_hi:[1,0]
	v_pk_mul_f32 v[4:5], v[4:5], v[42:43] op_sel_hi:[1,0]
	v_pk_mul_f32 v[2:3], v[2:3], v[42:43] op_sel_hi:[1,0]
	v_pk_mul_f32 v[0:1], v[0:1], v[42:43] op_sel_hi:[1,0]
	v_cvt_pk_bf16_f32 v35, v110, v111
	v_cvt_pk_bf16_f32 v34, v108, v109
	v_cvt_pk_bf16_f32 v33, v104, v107
	v_mov_b32_e32 v32, v244
	v_sub_f32_e32 v47, v47, v105
	v_exp_f32_e32 v106, v106
	v_exp_f32_e32 v44, v44
	v_exp_f32_e32 v45, v45
	v_exp_f32_e32 v46, v46
	v_mfma_f32_32x32x16_bf16 v[16:31], v[144:147], v[32:35], v[16:31]
	v_exp_f32_e32 v47, v47
	v_bfe_u32 v199, v45, 16, 1
	v_bfe_u32 v202, v171, 16, 1
	v_bfe_u32 v203, v106, 16, 1
	v_bfe_u32 v204, v44, 16, 1
	v_mfma_f32_32x32x16_bf16 v[0:15], v[172:175], v[32:35], v[0:15]
	v_bfe_u32 v205, v46, 16, 1
	v_bfe_u32 v198, v47, 16, 1
	v_add3_u32 v197, v45, v199, s59
	v_add3_u32 v199, v46, v205, s59
	v_add3_u32 v200, v44, v204, s59
	v_add3_u32 v201, v106, v203, s59
	v_add3_u32 v202, v171, v202, s59
	v_add3_u32 v198, v47, v198, s59
	v_add_f32_e32 v37, v104, v222
	v_lshrrev_b32_e32 v144, 16, v199
	v_cvt_pk_bf16_f32 v35, v46, v47
	v_cvt_pk_bf16_f32 v34, v44, v45
	v_cvt_pk_bf16_f32 v33, v106, v43
	v_cvt_pk_bf16_f32 v32, v171, v196
	v_add_f32_e32 v104, v107, v37
	v_sub_f32_e32 v48, v48, v105
	v_mfma_f32_32x32x16_bf16 v[16:31], v[148:151], v[32:35], v[16:31]
	v_sub_f32_e32 v49, v49, v105
	v_sub_f32_e32 v50, v50, v105
	v_sub_f32_e32 v51, v51, v105
	v_sub_f32_e32 v52, v52, v105
	v_sub_f32_e32 v53, v53, v105
	v_sub_f32_e32 v54, v54, v105
	v_sub_f32_e32 v55, v55, v105
	v_mfma_f32_32x32x16_bf16 v[0:15], v[176:179], v[32:35], v[0:15]
	v_add_f32_e32 v32, v108, v104
	v_add_f32_e32 v32, v109, v32
	v_add_f32_e32 v32, v110, v32
	v_add_f32_e32 v32, v111, v32
	v_add_f32_e32 v32, v171, v32
	v_sub_f32_e32 v56, v56, v105
	v_exp_f32_e32 v48, v48
	v_exp_f32_e32 v49, v49
	v_exp_f32_e32 v50, v50
	v_exp_f32_e32 v51, v51
	v_exp_f32_e32 v52, v52
	v_exp_f32_e32 v53, v53
	v_exp_f32_e32 v54, v54
	v_add_f32_e32 v32, v196, v32
	v_exp_f32_e32 v55, v55
	v_exp_f32_e32 v56, v56
	v_add_f32_e32 v32, v106, v32
	v_add_f32_e32 v32, v43, v32
	v_add_f32_e32 v32, v44, v32
	v_bfe_u32 v207, v53, 16, 1
	v_bfe_u32 v208, v51, 16, 1
	v_bfe_u32 v209, v49, 16, 1
	v_bfe_u32 v210, v48, 16, 1
	v_bfe_u32 v211, v50, 16, 1
	v_bfe_u32 v212, v52, 16, 1
	v_bfe_u32 v213, v54, 16, 1
	v_add_f32_e32 v32, v45, v32
	v_bfe_u32 v206, v55, 16, 1
	v_bfe_u32 v218, v56, 16, 1
	v_add3_u32 v203, v49, v209, s59
	v_add3_u32 v204, v51, v208, s59
	v_add3_u32 v205, v53, v207, s59
	v_add3_u32 v207, v54, v213, s59
	v_add3_u32 v208, v52, v212, s59
	v_add3_u32 v209, v50, v211, s59
	v_add3_u32 v210, v48, v210, s59
	v_add_f32_e32 v32, v46, v32
	v_add3_u32 v206, v55, v206, s59
	v_lshrrev_b32_e32 v145, 16, v210
	v_lshrrev_b32_e32 v146, 16, v209
	v_lshrrev_b32_e32 v147, 16, v208
	v_lshrrev_b32_e32 v172, 16, v207
	v_add_f32_e32 v32, v47, v32
	v_sub_f32_e32 v57, v57, v105
	v_sub_f32_e32 v58, v58, v105
	v_sub_f32_e32 v59, v59, v105
	v_sub_f32_e32 v60, v60, v105
	v_sub_f32_e32 v61, v61, v105
	v_sub_f32_e32 v62, v62, v105
	v_cvt_pk_bf16_f32 v37, v54, v55
	v_cvt_pk_bf16_f32 v36, v52, v53
	v_cvt_pk_bf16_f32 v35, v50, v51
	v_cvt_pk_bf16_f32 v34, v48, v49
	v_add_f32_e32 v32, v48, v32
	v_sub_f32_e32 v63, v63, v105
	v_exp_f32_e32 v57, v57
	v_exp_f32_e32 v58, v58
	v_exp_f32_e32 v59, v59
	v_exp_f32_e32 v60, v60
	v_exp_f32_e32 v61, v61
	v_exp_f32_e32 v62, v62
	v_mfma_f32_32x32x16_bf16 v[16:31], v[180:183], v[34:37], v[16:31]
	v_add_f32_e32 v32, v49, v32
	v_exp_f32_e32 v63, v63
	v_add_f32_e32 v32, v50, v32
	v_add_f32_e32 v32, v51, v32
	v_add_f32_e32 v32, v52, v32
	v_bfe_u32 v215, v61, 16, 1
	v_bfe_u32 v216, v59, 16, 1
	v_mfma_f32_32x32x16_bf16 v[0:15], v[184:187], v[34:37], v[0:15]
	v_bfe_u32 v217, v57, 16, 1
	v_bfe_u32 v219, v58, 16, 1
	v_bfe_u32 v220, v60, 16, 1
	v_bfe_u32 v221, v62, 16, 1
	v_add_f32_e32 v32, v53, v32
	v_bfe_u32 v214, v63, 16, 1
	v_add3_u32 v211, v57, v217, s59
	v_add3_u32 v212, v59, v216, s59
	v_add3_u32 v213, v61, v215, s59
	v_add3_u32 v215, v62, v221, s59
	v_add3_u32 v216, v60, v220, s59
	v_add3_u32 v217, v58, v219, s59
	v_add_f32_e32 v32, v54, v32
	v_add3_u32 v214, v63, v214, s59
	v_add_f32_e32 v32, v55, v32
	v_cvt_pk_bf16_f32 v41, v62, v63
	v_cvt_pk_bf16_f32 v40, v60, v61
	v_cvt_pk_bf16_f32 v39, v58, v59
	v_cvt_pk_bf16_f32 v38, v56, v57
	v_add_f32_e32 v32, v56, v32
	v_add_f32_e32 v32, v57, v32
	v_mfma_f32_32x32x16_bf16 v[16:31], v[188:191], v[38:41], v[16:31]
	v_add_f32_e32 v32, v58, v32
	v_add_f32_e32 v32, v59, v32
	v_add_f32_e32 v32, v60, v32
	v_add_f32_e32 v32, v61, v32
	v_add_f32_e32 v32, v62, v32
	v_add_f32_e32 v104, v63, v32
	v_fmac_f32_e32 v104, v170, v42
	v_mfma_f32_32x32x16_bf16 v[0:15], v[192:195], v[38:41], v[0:15]
	s_cbranch_scc1 .LBB0_704
	s_barrier
	s_waitcnt vmcnt(0)
	ds_write_b128 v165, v[224:227]
	ds_write_b128 v166, v[228:231]
	ds_write_b128 v167, v[232:235]
	ds_write_b128 v168, v[236:239] offset:13312
	ds_write_b128 v169, v[240:243] offset:13312
	s_waitcnt lgkmcnt(0)
	s_barrier
	ds_read_b128 v[32:35], v164
	ds_read_b128 v[36:39], v164 offset:32
	s_waitcnt lgkmcnt(1)
	v_mfma_f32_32x32x16_bf16 v[48:63], v[32:35], v[84:87], 0
	s_waitcnt lgkmcnt(0)
	v_mfma_f32_32x32x16_bf16 v[48:63], v[36:39], v[80:83], v[48:63]
	ds_read_b128 v[32:35], v164 offset:64
	ds_read_b128 v[36:39], v164 offset:96
	s_waitcnt lgkmcnt(1)
	v_mfma_f32_32x32x16_bf16 v[48:63], v[32:35], v[76:79], v[48:63]
	s_waitcnt lgkmcnt(0)
	v_mfma_f32_32x32x16_bf16 v[48:63], v[36:39], v[72:75], v[48:63]
	ds_read_b128 v[32:35], v164 offset:128
	ds_read_b128 v[36:39], v164 offset:160
	s_waitcnt lgkmcnt(1)
	v_mfma_f32_32x32x16_bf16 v[48:63], v[32:35], v[68:71], v[48:63]
	ds_read_b128 v[32:35], v164 offset:6656
	ds_read_b128 v[88:91], v164 offset:6688
	s_waitcnt lgkmcnt(2)
	v_mfma_f32_32x32x16_bf16 v[48:63], v[36:39], v[64:67], v[48:63]
	s_waitcnt lgkmcnt(1)
	v_mfma_f32_32x32x16_bf16 v[32:47], v[32:35], v[84:87], 0
	s_waitcnt lgkmcnt(0)
	v_mfma_f32_32x32x16_bf16 v[32:47], v[88:91], v[80:83], v[32:47]
	ds_read_b128 v[80:83], v164 offset:6720
	ds_read_b128 v[84:87], v164 offset:6752
	s_waitcnt lgkmcnt(1)
	v_mfma_f32_32x32x16_bf16 v[32:47], v[80:83], v[76:79], v[32:47]
	s_nop 3
	v_max_f32_e32 v80, v49, v49
	v_max_f32_e32 v81, v48, v48
	v_max_f32_e32 v80, v81, v80
	s_waitcnt lgkmcnt(0)
	v_mfma_f32_32x32x16_bf16 v[32:47], v[84:87], v[72:75], v[32:47]
	ds_read_b128 v[72:75], v164 offset:6784
	ds_read_b128 v[76:79], v164 offset:6816
	s_waitcnt lgkmcnt(1)
	v_mfma_f32_32x32x16_bf16 v[32:47], v[72:75], v[68:71], v[32:47]
	v_max3_f32 v68, v80, v50, v51
	v_max3_f32 v68, v68, v52, v53
	v_max3_f32 v68, v68, v54, v55
	v_max3_f32 v68, v68, v56, v57
	v_max3_f32 v68, v68, v58, v59
	v_max3_f32 v68, v68, v60, v61
	v_max3_f32 v68, v68, v62, v63
	s_waitcnt lgkmcnt(0)
	v_mfma_f32_32x32x16_bf16 v[32:47], v[76:79], v[64:67], v[32:47]
	s_nop 11
	v_max3_f32 v64, v68, v32, v33
	v_max3_f32 v64, v64, v34, v35
	v_max3_f32 v64, v64, v36, v37
	v_max3_f32 v64, v64, v38, v39
	v_max3_f32 v64, v64, v40, v41
	v_max3_f32 v64, v64, v42, v43
	v_max3_f32 v64, v64, v44, v45
	v_max3_f32 v64, v64, v46, v47
	ds_bpermute_b32 v65, v123, v64
	s_waitcnt lgkmcnt(0)
	v_max3_f32 v65, v105, v64, v65
	v_sub_f32_e32 v32, v32, v65
	v_exp_f32_e32 v66, v32
	v_sub_f32_e32 v32, v33, v65
	v_exp_f32_e32 v67, v32
	v_sub_f32_e32 v32, v34, v65
	v_exp_f32_e32 v68, v32
	v_sub_f32_e32 v32, v35, v65
	v_exp_f32_e32 v69, v32
	v_sub_f32_e32 v32, v36, v65
	v_exp_f32_e32 v70, v32
	v_sub_f32_e32 v32, v37, v65
	v_exp_f32_e32 v71, v32
	v_sub_f32_e32 v32, v38, v65
	v_exp_f32_e32 v72, v32
	v_sub_f32_e32 v32, v39, v65
	v_exp_f32_e32 v73, v32
	v_sub_f32_e32 v32, v40, v65
	v_exp_f32_e32 v74, v32
	v_sub_f32_e32 v32, v41, v65
	v_exp_f32_e32 v75, v32
	v_sub_f32_e32 v32, v42, v65
	v_sub_f32_e32 v48, v48, v65
	v_exp_f32_e32 v76, v32
	v_sub_f32_e32 v32, v43, v65
	v_exp_f32_e32 v48, v48
	v_sub_f32_e32 v49, v49, v65
	v_exp_f32_e32 v77, v32
	v_sub_f32_e32 v32, v44, v65
	v_exp_f32_e32 v49, v49
	v_sub_f32_e32 v50, v50, v65
	v_sub_f32_e32 v55, v55, v65
	v_exp_f32_e32 v78, v32
	v_sub_f32_e32 v32, v45, v65
	v_exp_f32_e32 v50, v50
	v_sub_f32_e32 v51, v51, v65
	v_sub_f32_e32 v53, v53, v65
	v_exp_f32_e32 v55, v55
	v_exp_f32_e32 v79, v32
	v_sub_f32_e32 v32, v46, v65
	v_exp_f32_e32 v51, v51
	v_sub_f32_e32 v52, v52, v65
	v_exp_f32_e32 v53, v53
	v_sub_f32_e32 v54, v54, v65
	v_exp_f32_e32 v80, v32
	v_sub_f32_e32 v32, v47, v65
	v_sub_f32_e32 v64, v105, v65
	v_exp_f32_e32 v52, v52
	v_exp_f32_e32 v54, v54
	v_sub_f32_e32 v56, v56, v65
	v_sub_f32_e32 v57, v57, v65
	v_sub_f32_e32 v58, v58, v65
	v_sub_f32_e32 v59, v59, v65
	v_sub_f32_e32 v60, v60, v65
	v_sub_f32_e32 v61, v61, v65
	v_sub_f32_e32 v62, v62, v65
	v_sub_f32_e32 v63, v63, v65
	v_exp_f32_e32 v65, v32
	v_add_f32_e32 v32, 0, v48
	v_add_f32_e32 v32, v49, v32
	v_add_f32_e32 v44, v50, v32
	ds_read2_b64 v[32:35], v143 offset0:128 offset1:130
	v_exp_f32_e32 v64, v64
	v_cvt_pk_bf16_f32 v39, v54, v55
	v_cvt_pk_bf16_f32 v38, v52, v53
	v_cvt_pk_bf16_f32 v37, v50, v51
	v_cvt_pk_bf16_f32 v36, v48, v49
	ds_read2_b64 v[40:43], v142 offset0:128 offset1:130
	v_pk_mul_f32 v[30:31], v[30:31], v[64:65] op_sel_hi:[1,0]
	v_pk_mul_f32 v[28:29], v[28:29], v[64:65] op_sel_hi:[1,0]
	v_pk_mul_f32 v[26:27], v[26:27], v[64:65] op_sel_hi:[1,0]
	v_pk_mul_f32 v[24:25], v[24:25], v[64:65] op_sel_hi:[1,0]
	v_pk_mul_f32 v[22:23], v[22:23], v[64:65] op_sel_hi:[1,0]
	v_pk_mul_f32 v[20:21], v[20:21], v[64:65] op_sel_hi:[1,0]
	v_pk_mul_f32 v[18:19], v[18:19], v[64:65] op_sel_hi:[1,0]
	v_pk_mul_f32 v[16:17], v[16:17], v[64:65] op_sel_hi:[1,0]
	v_exp_f32_e32 v57, v57
	v_exp_f32_e32 v59, v59
	s_waitcnt lgkmcnt(1)
	v_mfma_f32_32x32x16_bf16 v[16:31], v[32:35], v[36:39], v[16:31]
	v_add_f32_e32 v32, v51, v44
	v_exp_f32_e32 v56, v56
	v_exp_f32_e32 v58, v58
	v_exp_f32_e32 v60, v60
	v_exp_f32_e32 v62, v62
	v_add_f32_e32 v32, v52, v32
	v_exp_f32_e32 v61, v61
	v_exp_f32_e32 v63, v63
	v_add_f32_e32 v32, v53, v32
	v_pk_mul_f32 v[14:15], v[14:15], v[64:65] op_sel_hi:[1,0]
	v_pk_mul_f32 v[12:13], v[12:13], v[64:65] op_sel_hi:[1,0]
	v_pk_mul_f32 v[10:11], v[10:11], v[64:65] op_sel_hi:[1,0]
	v_pk_mul_f32 v[8:9], v[8:9], v[64:65] op_sel_hi:[1,0]
	v_pk_mul_f32 v[6:7], v[6:7], v[64:65] op_sel_hi:[1,0]
	v_pk_mul_f32 v[4:5], v[4:5], v[64:65] op_sel_hi:[1,0]
	v_pk_mul_f32 v[2:3], v[2:3], v[64:65] op_sel_hi:[1,0]
	v_pk_mul_f32 v[0:1], v[0:1], v[64:65] op_sel_hi:[1,0]
	v_add_f32_e32 v32, v54, v32
	v_add_f32_e32 v48, v55, v32
	s_waitcnt lgkmcnt(0)
	v_mfma_f32_32x32x16_bf16 v[0:15], v[40:43], v[36:39], v[0:15]
	ds_read2_b64 v[32:35], v143 offset0:132 offset1:134
	ds_read2_b64 v[44:47], v142 offset0:132 offset1:134
	v_add_f32_e32 v40, v56, v48
	v_bfe_u32 v38, v56, 16, 1
	v_bfe_u32 v39, v58, 16, 1
	v_bfe_u32 v48, v62, 16, 1
	v_add3_u32 v48, v62, v48, s59
	v_add3_u32 v39, v58, v39, s59
	v_add3_u32 v38, v56, v38, s59
	v_lshrrev_b32_e32 v49, 16, v38
	v_lshrrev_b32_e32 v50, 16, v39
	v_cvt_pk_bf16_f32 v39, v62, v63
	v_cvt_pk_bf16_f32 v38, v60, v61
	v_cvt_pk_bf16_f32 v37, v58, v59
	v_cvt_pk_bf16_f32 v36, v56, v57
	s_waitcnt lgkmcnt(1)
	s_nop 0
	v_mfma_f32_32x32x16_bf16 v[16:31], v[32:35], v[36:39], v[16:31]
	v_add_f32_e32 v32, v57, v40
	v_add_f32_e32 v32, v58, v32
	v_add_f32_e32 v32, v59, v32
	v_add_f32_e32 v32, v60, v32
	v_add_f32_e32 v32, v61, v32
	v_add_f32_e32 v32, v62, v32
	v_add_f32_e32 v32, v63, v32
	s_waitcnt lgkmcnt(0)
	v_mfma_f32_32x32x16_bf16 v[0:15], v[44:47], v[36:39], v[0:15]
	v_add_f32_e32 v44, v66, v32
	ds_read2_b64 v[32:35], v143 offset0:136 offset1:138
	v_cvt_pk_bf16_f32 v39, v72, v73
	v_cvt_pk_bf16_f32 v38, v70, v71
	v_cvt_pk_bf16_f32 v37, v68, v69
	v_cvt_pk_bf16_f32 v36, v66, v67
	ds_read2_b64 v[40:43], v142 offset0:136 offset1:138
	s_waitcnt lgkmcnt(1)
	v_mfma_f32_32x32x16_bf16 v[16:31], v[32:35], v[36:39], v[16:31]
	v_add_f32_e32 v32, v67, v44
	v_add_f32_e32 v32, v68, v32
	v_add_f32_e32 v32, v69, v32
	v_add_f32_e32 v32, v70, v32
	v_add_f32_e32 v32, v71, v32
	v_add_f32_e32 v32, v72, v32
	v_add_f32_e32 v32, v73, v32
	v_add_f32_e32 v32, v74, v32
	v_add_f32_e32 v32, v75, v32
	v_add_f32_e32 v32, v76, v32
	v_add_f32_e32 v32, v77, v32
	v_add_f32_e32 v32, v78, v32
	v_add_f32_e32 v32, v79, v32
	v_add_f32_e32 v32, v80, v32
	s_waitcnt lgkmcnt(0)
	v_mfma_f32_32x32x16_bf16 v[0:15], v[40:43], v[36:39], v[0:15]
	v_add_f32_e32 v40, v65, v32
	v_bfe_u32 v32, v74, 16, 1
	v_bfe_u32 v33, v76, 16, 1
	v_add3_u32 v33, v76, v33, s59
	v_add3_u32 v32, v74, v32, s59
	v_lshrrev_b32_e32 v43, 16, v32
	v_lshrrev_b32_e32 v44, 16, v33
	ds_read2_b64 v[32:35], v141 offset0:140 offset1:142
	v_fmac_f32_e32 v40, v104, v64
	v_cvt_pk_bf16_f32 v39, v80, v65
	ds_bpermute_b32 v41, v123, v40
	v_cvt_pk_bf16_f32 v38, v78, v79
	v_cvt_pk_bf16_f32 v37, v76, v77
	v_cvt_pk_bf16_f32 v36, v74, v75
	v_mov_b32_e32 v123, v117
	s_waitcnt lgkmcnt(0)
	v_add_f32_e32 v40, v40, v41
	v_mfma_f32_32x32x16_bf16 v[16:31], v[32:35], v[36:39], v[16:31]
	ds_read2_b64 v[32:35], v140 offset0:140 offset1:142
	v_div_scale_f32 v41, s[0:1], v40, v40, 1.0
	v_rcp_f32_e32 v42, v41
	s_waitcnt lgkmcnt(0)
	v_mfma_f32_32x32x16_bf16 v[0:15], v[32:35], v[36:39], v[0:15]
	v_fma_f32 v32, -v41, v42, 1.0
	v_fmac_f32_e32 v42, v32, v42
	v_div_scale_f32 v32, vcc, 1.0, v40, 1.0
	v_mul_f32_e32 v33, v32, v42
	v_fma_f32 v34, -v41, v33, v32
	v_fmac_f32_e32 v33, v34, v42
	v_fma_f32 v32, -v41, v33, v32
	v_div_fmas_f32 v32, v32, v42, v33
	v_div_fixup_f32 v32, v32, v40, 1.0
	v_mov_b32_e32 v38, v16
	v_mov_b32_e32 v39, v18
	v_mov_b32_e32 v18, v17
	v_lshlrev_b64 v[34:35], 11, v[118:119]
	v_pk_mul_f32 v[38:39], v[38:39], v[32:33] op_sel_hi:[1,0]
	v_pk_mul_f32 v[16:17], v[18:19], v[32:33] op_sel_hi:[1,0]
	v_lshl_add_u64 v[34:35], s[8:9], 0, v[34:35]
	v_and_b32_sdwa v19, v38, v159 dst_sel:DWORD dst_unused:UNUSED_PAD src0_sel:WORD_1 src1_sel:DWORD
	v_and_b32_sdwa v33, v17, v159 dst_sel:DWORD dst_unused:UNUSED_PAD src0_sel:WORD_1 src1_sel:DWORD
	v_lshl_add_u64 v[34:35], v[120:121], 1, v[34:35]
	v_and_b32_sdwa v18, v39, v159 dst_sel:DWORD dst_unused:UNUSED_PAD src0_sel:WORD_1 src1_sel:DWORD
	v_add3_u32 v19, v38, v19, s59
	v_and_b32_sdwa v38, v16, v159 dst_sel:DWORD dst_unused:UNUSED_PAD src0_sel:WORD_1 src1_sel:DWORD
	v_add3_u32 v17, v17, v33, s59
	v_lshl_add_u64 v[34:35], v[34:35], 0, v[122:123]
	v_add3_u32 v18, v39, v18, s59
	v_add3_u32 v16, v16, v38, s59
	v_and_b32_e32 v17, 0xffff0000, v17
	v_and_b32_e32 v16, 0xffff0000, v16
	v_or_b32_sdwa v17, v17, v18 dst_sel:DWORD dst_unused:UNUSED_PAD src0_sel:DWORD src1_sel:WORD_1
	v_add_co_u32_e32 v18, vcc, s61, v34
	v_or_b32_sdwa v16, v16, v19 dst_sel:DWORD dst_unused:UNUSED_PAD src0_sel:DWORD src1_sel:WORD_1
	s_nop 0
	v_addc_co_u32_e32 v19, vcc, 0, v35, vcc
	global_store_dwordx2 v[18:19], v[16:17], off offset:3840
	v_mov_b32_e32 v16, v20
	v_mov_b32_e32 v17, v22
	v_pk_mul_f32 v[16:17], v[16:17], v[32:33] op_sel_hi:[1,0]
	v_mov_b32_e32 v22, v21
	v_pk_mul_f32 v[18:19], v[22:23], v[32:33] op_sel_hi:[1,0]
	v_and_b32_sdwa v20, v17, v159 dst_sel:DWORD dst_unused:UNUSED_PAD src0_sel:WORD_1 src1_sel:DWORD
	v_and_b32_sdwa v21, v16, v159 dst_sel:DWORD dst_unused:UNUSED_PAD src0_sel:WORD_1 src1_sel:DWORD
	v_add3_u32 v16, v16, v21, s59
	v_add3_u32 v17, v17, v20, s59
	v_and_b32_sdwa v20, v19, v159 dst_sel:DWORD dst_unused:UNUSED_PAD src0_sel:WORD_1 src1_sel:DWORD
	v_and_b32_sdwa v21, v18, v159 dst_sel:DWORD dst_unused:UNUSED_PAD src0_sel:WORD_1 src1_sel:DWORD
	v_add3_u32 v19, v19, v20, s59
	v_add3_u32 v18, v18, v21, s59
	v_and_b32_e32 v19, 0xffff0000, v19
	v_and_b32_e32 v18, 0xffff0000, v18
	v_lshl_add_u64 v[36:37], v[34:35], 0, s[48:49]
	v_or_b32_sdwa v17, v19, v17 dst_sel:DWORD dst_unused:UNUSED_PAD src0_sel:DWORD src1_sel:WORD_1
	v_or_b32_sdwa v16, v18, v16 dst_sel:DWORD dst_unused:UNUSED_PAD src0_sel:DWORD src1_sel:WORD_1
	global_store_dwordx2 v[36:37], v[16:17], off offset:16
	v_mov_b32_e32 v16, v24
	v_mov_b32_e32 v17, v26
	v_pk_mul_f32 v[16:17], v[16:17], v[32:33] op_sel_hi:[1,0]
	v_mov_b32_e32 v26, v25
	v_pk_mul_f32 v[18:19], v[26:27], v[32:33] op_sel_hi:[1,0]
	v_and_b32_sdwa v20, v17, v159 dst_sel:DWORD dst_unused:UNUSED_PAD src0_sel:WORD_1 src1_sel:DWORD
	v_and_b32_sdwa v21, v16, v159 dst_sel:DWORD dst_unused:UNUSED_PAD src0_sel:WORD_1 src1_sel:DWORD
	v_add3_u32 v16, v16, v21, s59
	v_add3_u32 v17, v17, v20, s59
	v_and_b32_sdwa v20, v19, v159 dst_sel:DWORD dst_unused:UNUSED_PAD src0_sel:WORD_1 src1_sel:DWORD
	v_and_b32_sdwa v21, v18, v159 dst_sel:DWORD dst_unused:UNUSED_PAD src0_sel:WORD_1 src1_sel:DWORD
	v_add3_u32 v19, v19, v20, s59
	v_add3_u32 v18, v18, v21, s59
	v_and_b32_e32 v19, 0xffff0000, v19
	v_and_b32_e32 v18, 0xffff0000, v18
	v_or_b32_sdwa v17, v19, v17 dst_sel:DWORD dst_unused:UNUSED_PAD src0_sel:DWORD src1_sel:WORD_1
	v_or_b32_sdwa v16, v18, v16 dst_sel:DWORD dst_unused:UNUSED_PAD src0_sel:DWORD src1_sel:WORD_1
	global_store_dwordx2 v[36:37], v[16:17], off offset:32
	v_mov_b32_e32 v16, v28
	v_mov_b32_e32 v17, v30
	v_pk_mul_f32 v[16:17], v[16:17], v[32:33] op_sel_hi:[1,0]
	v_mov_b32_e32 v30, v29
	v_pk_mul_f32 v[18:19], v[30:31], v[32:33] op_sel_hi:[1,0]
	v_and_b32_sdwa v20, v17, v159 dst_sel:DWORD dst_unused:UNUSED_PAD src0_sel:WORD_1 src1_sel:DWORD
	v_and_b32_sdwa v21, v16, v159 dst_sel:DWORD dst_unused:UNUSED_PAD src0_sel:WORD_1 src1_sel:DWORD
	v_add3_u32 v16, v16, v21, s59
	v_add3_u32 v17, v17, v20, s59
	v_and_b32_sdwa v20, v19, v159 dst_sel:DWORD dst_unused:UNUSED_PAD src0_sel:WORD_1 src1_sel:DWORD
	v_and_b32_sdwa v21, v18, v159 dst_sel:DWORD dst_unused:UNUSED_PAD src0_sel:WORD_1 src1_sel:DWORD
	v_add3_u32 v19, v19, v20, s59
	v_add3_u32 v18, v18, v21, s59
	v_and_b32_e32 v19, 0xffff0000, v19
	v_and_b32_e32 v18, 0xffff0000, v18
	v_or_b32_sdwa v17, v19, v17 dst_sel:DWORD dst_unused:UNUSED_PAD src0_sel:DWORD src1_sel:WORD_1
	v_or_b32_sdwa v16, v18, v16 dst_sel:DWORD dst_unused:UNUSED_PAD src0_sel:DWORD src1_sel:WORD_1
	global_store_dwordx2 v[36:37], v[16:17], off offset:48
	v_mov_b32_e32 v16, v0
	v_mov_b32_e32 v17, v2
	v_pk_mul_f32 v[16:17], v[16:17], v[32:33] op_sel_hi:[1,0]
	v_mov_b32_e32 v2, v1
	v_pk_mul_f32 v[0:1], v[2:3], v[32:33] op_sel_hi:[1,0]
	v_and_b32_sdwa v2, v17, v159 dst_sel:DWORD dst_unused:UNUSED_PAD src0_sel:WORD_1 src1_sel:DWORD
	v_and_b32_sdwa v3, v16, v159 dst_sel:DWORD dst_unused:UNUSED_PAD src0_sel:WORD_1 src1_sel:DWORD
	v_add3_u32 v3, v16, v3, s59
	v_add3_u32 v2, v17, v2, s59
	v_and_b32_sdwa v16, v1, v159 dst_sel:DWORD dst_unused:UNUSED_PAD src0_sel:WORD_1 src1_sel:DWORD
	v_and_b32_sdwa v17, v0, v159 dst_sel:DWORD dst_unused:UNUSED_PAD src0_sel:WORD_1 src1_sel:DWORD
	v_add3_u32 v1, v1, v16, s59
	v_add3_u32 v0, v0, v17, s59
	v_and_b32_e32 v1, 0xffff0000, v1
	v_and_b32_e32 v0, 0xffff0000, v0
	v_or_b32_sdwa v1, v1, v2 dst_sel:DWORD dst_unused:UNUSED_PAD src0_sel:DWORD src1_sel:WORD_1
	v_or_b32_sdwa v0, v0, v3 dst_sel:DWORD dst_unused:UNUSED_PAD src0_sel:DWORD src1_sel:WORD_1
	global_store_dwordx2 v[36:37], v[0:1], off offset:64
	v_mov_b32_e32 v0, v4
	v_mov_b32_e32 v1, v6
	v_pk_mul_f32 v[0:1], v[0:1], v[32:33] op_sel_hi:[1,0]
	v_mov_b32_e32 v6, v5
	v_pk_mul_f32 v[2:3], v[6:7], v[32:33] op_sel_hi:[1,0]
	v_and_b32_sdwa v4, v1, v159 dst_sel:DWORD dst_unused:UNUSED_PAD src0_sel:WORD_1 src1_sel:DWORD
	v_and_b32_sdwa v5, v0, v159 dst_sel:DWORD dst_unused:UNUSED_PAD src0_sel:WORD_1 src1_sel:DWORD
	v_add3_u32 v0, v0, v5, s59
	v_add3_u32 v1, v1, v4, s59
	v_and_b32_sdwa v4, v3, v159 dst_sel:DWORD dst_unused:UNUSED_PAD src0_sel:WORD_1 src1_sel:DWORD
	v_and_b32_sdwa v5, v2, v159 dst_sel:DWORD dst_unused:UNUSED_PAD src0_sel:WORD_1 src1_sel:DWORD
	v_add3_u32 v3, v3, v4, s59
	v_add3_u32 v2, v2, v5, s59
	v_and_b32_e32 v3, 0xffff0000, v3
	v_and_b32_e32 v2, 0xffff0000, v2
	v_or_b32_sdwa v1, v3, v1 dst_sel:DWORD dst_unused:UNUSED_PAD src0_sel:DWORD src1_sel:WORD_1
	v_or_b32_sdwa v0, v2, v0 dst_sel:DWORD dst_unused:UNUSED_PAD src0_sel:DWORD src1_sel:WORD_1
	global_store_dwordx2 v[36:37], v[0:1], off offset:80
	v_mov_b32_e32 v0, v8
	v_mov_b32_e32 v1, v10
	v_pk_mul_f32 v[0:1], v[0:1], v[32:33] op_sel_hi:[1,0]
	v_mov_b32_e32 v10, v9
	v_pk_mul_f32 v[2:3], v[10:11], v[32:33] op_sel_hi:[1,0]
	v_and_b32_sdwa v4, v1, v159 dst_sel:DWORD dst_unused:UNUSED_PAD src0_sel:WORD_1 src1_sel:DWORD
	v_and_b32_sdwa v5, v0, v159 dst_sel:DWORD dst_unused:UNUSED_PAD src0_sel:WORD_1 src1_sel:DWORD
	v_add3_u32 v0, v0, v5, s59
	v_add3_u32 v1, v1, v4, s59
	v_and_b32_sdwa v4, v3, v159 dst_sel:DWORD dst_unused:UNUSED_PAD src0_sel:WORD_1 src1_sel:DWORD
	v_and_b32_sdwa v5, v2, v159 dst_sel:DWORD dst_unused:UNUSED_PAD src0_sel:WORD_1 src1_sel:DWORD
	v_add3_u32 v3, v3, v4, s59
	v_add3_u32 v2, v2, v5, s59
	v_and_b32_e32 v3, 0xffff0000, v3
	v_and_b32_e32 v2, 0xffff0000, v2
	v_or_b32_sdwa v1, v3, v1 dst_sel:DWORD dst_unused:UNUSED_PAD src0_sel:DWORD src1_sel:WORD_1
	v_or_b32_sdwa v0, v2, v0 dst_sel:DWORD dst_unused:UNUSED_PAD src0_sel:DWORD src1_sel:WORD_1
	global_store_dwordx2 v[36:37], v[0:1], off offset:96
	v_mov_b32_e32 v0, v12
	v_mov_b32_e32 v1, v14
	v_pk_mul_f32 v[0:1], v[0:1], v[32:33] op_sel_hi:[1,0]
	v_mov_b32_e32 v14, v13
	v_pk_mul_f32 v[2:3], v[14:15], v[32:33] op_sel_hi:[1,0]
	v_and_b32_sdwa v4, v1, v159 dst_sel:DWORD dst_unused:UNUSED_PAD src0_sel:WORD_1 src1_sel:DWORD
	v_and_b32_sdwa v5, v0, v159 dst_sel:DWORD dst_unused:UNUSED_PAD src0_sel:WORD_1 src1_sel:DWORD
	v_add3_u32 v0, v0, v5, s59
	v_add3_u32 v1, v1, v4, s59
	v_and_b32_sdwa v4, v3, v159 dst_sel:DWORD dst_unused:UNUSED_PAD src0_sel:WORD_1 src1_sel:DWORD
	v_and_b32_sdwa v5, v2, v159 dst_sel:DWORD dst_unused:UNUSED_PAD src0_sel:WORD_1 src1_sel:DWORD
	v_add3_u32 v3, v3, v4, s59
	v_add3_u32 v2, v2, v5, s59
	v_and_b32_e32 v3, 0xffff0000, v3
	v_and_b32_e32 v2, 0xffff0000, v2
	v_or_b32_sdwa v1, v3, v1 dst_sel:DWORD dst_unused:UNUSED_PAD src0_sel:DWORD src1_sel:WORD_1
	v_or_b32_sdwa v0, v2, v0 dst_sel:DWORD dst_unused:UNUSED_PAD src0_sel:DWORD src1_sel:WORD_1
	global_store_dwordx2 v[36:37], v[0:1], off offset:112
	s_branch .LBB0_579

.LBB0_1670:
	s_andn2_b64 vcc, exec, s[0:1]
	s_cbranch_vccnz .LBB0_1562
	s_mov_b64 s[8:9], s[30:31]
	s_lshl_b32 s0, s54, 7
	v_mov_b32_e32 v0, v117
	s_and_b32 s0, s0, 0x780
	s_ashr_i32 s52, s54, 6
	s_addk_i32 s0, 0x100
	s_bfe_u32 s53, s54, 0x20004
	v_mbcnt_lo_u32_b32 v0, -1, v0
	s_add_u32 s24, s8, 0x14297900
	v_mbcnt_hi_u32_b32 v0, -1, v0
	s_addc_u32 s25, s9, 0
	v_add_u32_e32 v2, s33, v0
	s_mul_i32 s34, s52, 0x900
	s_mul_hi_i32 s35, s52, 0x900
	s_add_u32 s0, s34, s0
	v_ashrrev_i32_e32 v0, 1, v2
	v_and_b32_e32 v3, 31, v2
	s_addc_u32 s1, s35, 0
	v_and_b32_e32 v0, 0xffffffe0, v0
	v_ashrrev_i32_e32 v1, 31, v0
	v_or_b32_e32 v4, s0, v3
	v_mov_b32_e32 v5, s1
	v_lshl_add_u64 v[118:119], v[4:5], 0, v[0:1]
	v_mov_b64_e32 v[0:1], s[8:9]
	v_mad_u64_u32 v[0:1], s[0:1], v118, s56, v[0:1]
	v_bfe_u32 v15, v2, 5, 1
	v_mad_i32_i24 v1, v119, s56, v1
	s_mul_i32 s16, s53, 0xc0
	v_lshl_add_u64 v[0:1], v[0:1], 0, s[16:17]
	v_lshlrev_b32_e32 v116, 4, v15
	v_lshl_add_u64 v[0:1], v[0:1], 0, v[116:117]
	v_lshl_add_u64 v[4:5], v[0:1], 0, s[40:41]
	v_add_co_u32_e32 v0, vcc, s71, v0
	s_add_u32 s26, s8, 0x13097900
	s_nop 0
	v_addc_co_u32_e32 v1, vcc, 0, v1, vcc
	global_load_dwordx4 v[80:83], v[4:5], off offset:32
	global_load_dwordx4 v[76:79], v[4:5], off offset:64
	global_load_dwordx4 v[72:75], v[4:5], off offset:96
	global_load_dwordx4 v[68:71], v[4:5], off offset:128
	global_load_dwordx4 v[84:87], v[0:1], off offset:2304
	global_load_dwordx4 v[64:67], v[4:5], off offset:160
	v_mul_hi_i32 v0, v2, s72
	v_lshrrev_b32_e32 v1, 31, v0
	v_ashrrev_i32_e32 v0, 1, v0
	v_add_u32_e32 v0, v0, v1
	v_mad_u64_u32 v[6:7], s[0:1], v0, -12, v[2:3]
	v_ashrrev_i32_e32 v1, 31, v0
	s_addc_u32 s27, s9, 0
	v_cmp_gt_i32_e32 vcc, 8, v6
	v_cmp_lt_i32_e64 s[0:1], 7, v6
	v_mad_i64_i32 v[10:11], s[4:5], s52, v152, v[0:1]
	s_and_saveexec_b64 s[4:5], s[0:1]
	s_xor_b64 s[0:1], exec, s[4:5]
	v_lshlrev_b64 v[4:5], 6, v[10:11]
	v_lshl_add_u64 v[4:5], s[24:25], 0, v[4:5]
	v_lshl_add_u32 v8, v6, 3, v156
	v_mov_b32_e32 v9, v117
	v_lshl_add_u64 v[8:9], v[8:9], 1, v[4:5]
	s_or_saveexec_b64 s[0:1], s[0:1]
	v_lshlrev_b32_e32 v4, 3, v6
	v_ashrrev_i32_e32 v5, 31, v4
	s_xor_b64 exec, exec, s[0:1]
	v_lshlrev_b64 v[8:9], 9, v[10:11]
	v_lshl_add_u64 v[8:9], s[26:27], 0, v[8:9]
	s_lshl_b32 s16, s53, 7
	v_lshl_add_u64 v[8:9], v[8:9], 0, s[16:17]
	v_lshl_add_u64 v[8:9], v[4:5], 1, v[8:9]
	s_or_b64 exec, exec, s[0:1]
	global_load_dwordx4 v[224:227], v[8:9], off
	v_add_u32_e32 v14, 0x100, v2
	v_mul_hi_i32 v7, v14, s72
	v_lshrrev_b32_e32 v8, 31, v7
	v_ashrrev_i32_e32 v7, 1, v7
	v_add_u32_e32 v8, v7, v8
	v_mad_u64_u32 v[12:13], s[0:1], v8, -12, v[14:15]
	v_ashrrev_i32_e32 v9, 31, v8
	v_cmp_gt_i32_e64 s[4:5], 8, v12
	v_cmp_lt_i32_e64 s[0:1], 7, v12
	v_lshl_add_u64 v[18:19], s[34:35], 0, v[8:9]
	s_and_saveexec_b64 s[6:7], s[0:1]
	s_xor_b64 s[0:1], exec, s[6:7]
	v_lshlrev_b64 v[10:11], 6, v[18:19]
	v_lshl_add_u64 v[10:11], s[24:25], 0, v[10:11]
	v_lshl_add_u32 v16, v12, 3, v156
	v_mov_b32_e32 v17, v117
	v_lshl_add_u64 v[16:17], v[16:17], 1, v[10:11]
	s_or_saveexec_b64 s[0:1], s[0:1]
	v_lshlrev_b32_e32 v10, 3, v12
	v_ashrrev_i32_e32 v11, 31, v10
	s_xor_b64 exec, exec, s[0:1]
	v_lshlrev_b64 v[16:17], 9, v[18:19]
	v_lshl_add_u64 v[16:17], s[26:27], 0, v[16:17]
	s_lshl_b32 s16, s53, 7
	v_lshl_add_u64 v[16:17], v[16:17], 0, s[16:17]
	v_lshl_add_u64 v[16:17], v[10:11], 1, v[16:17]
	s_or_b64 exec, exec, s[0:1]
	global_load_dwordx4 v[228:231], v[16:17], off
	v_add_u32_e32 v18, 0x200, v2
	v_mul_hi_i32 v7, v18, s72
	v_lshrrev_b32_e32 v13, 31, v7
	v_ashrrev_i32_e32 v7, 1, v7
	v_add_u32_e32 v16, v7, v13
	v_mad_u64_u32 v[22:23], s[0:1], v16, -12, v[18:19]
	v_ashrrev_i32_e32 v17, 31, v16
	v_lshlrev_b32_e32 v18, 3, v22
	v_cmp_gt_i32_e64 s[6:7], 8, v22
	v_cmp_lt_i32_e64 s[0:1], 7, v22
	v_lshl_add_u64 v[26:27], s[34:35], 0, v[16:17]
	v_subrev_u32_e32 v20, 64, v18
	v_ashrrev_i32_e32 v19, 31, v18
	s_and_saveexec_b64 s[34:35], s[0:1]
	s_xor_b64 s[0:1], exec, s[34:35]
	v_lshlrev_b64 v[24:25], 6, v[26:27]
	v_lshl_add_u64 v[24:25], s[24:25], 0, v[24:25]
	v_mov_b32_e32 v21, v117
	v_lshl_add_u64 v[24:25], v[20:21], 1, v[24:25]
	s_lshl_b32 s16, s53, 6
	s_or_saveexec_b64 s[0:1], s[0:1]
	v_mov_b64_e32 v[120:121], s[16:17]
	v_mov_b32_e32 v7, s16
	s_xor_b64 exec, exec, s[0:1]
	s_cbranch_execz .LBB0_1683
	v_lshlrev_b64 v[24:25], 9, v[26:27]
	v_lshl_add_u64 v[24:25], s[26:27], 0, v[24:25]
	s_lshl_b32 s24, s53, 7
	s_mov_b32 s25, s17
	s_lshl_b32 s16, s53, 6
	v_lshl_add_u64 v[24:25], v[24:25], 0, s[24:25]
	v_lshl_add_u64 v[24:25], v[18:19], 1, v[24:25]
	v_mov_b32_e32 v21, v117
	v_mov_b64_e32 v[120:121], s[16:17]
	v_mov_b32_e32 v7, s16
.LBB0_1683:
	s_or_b64 exec, exec, s[0:1]
	s_add_u32 s0, s8, 0x144d7900
	s_addc_u32 s1, s9, 0
	v_ashrrev_i32_e32 v13, 3, v2
	v_lshl_add_u32 v7, s52, 8, v7
	v_lshlrev_b32_e32 v2, 4, v2
	v_lshlrev_b32_e32 v122, 3, v15
	v_add_u32_e32 v15, v7, v13
	v_mov_b64_e32 v[26:27], s[0:1]
	v_and_b32_e32 v30, 0x70, v2
	v_ashrrev_i32_e32 v2, 3, v14
	v_mad_i64_i32 v[28:29], s[0:1], v15, s73, v[26:27]
	v_mov_b32_e32 v31, v117
	v_add_u32_e32 v7, v7, v2
	v_lshl_add_u64 v[28:29], v[28:29], 0, v[30:31]
	v_mad_i64_i32 v[26:27], s[0:1], v7, s73, v[26:27]
	global_load_dwordx4 v[232:235], v[24:25], off
	v_lshl_add_u64 v[26:27], v[26:27], 0, v[30:31]
	global_load_dwordx4 v[236:239], v[28:29], off
	global_load_dwordx4 v[240:243], v[26:27], off
	v_and_b32_e32 v23, 64, v157
	v_mad_i64_i32 v[24:25], s[24:25], v15, s73, 0
	v_mad_i64_i32 v[14:15], s[0:1], v7, s73, 0
	v_xor_b32_e32 v7, 32, v157
	v_add_u32_e32 v23, 64, v23
	v_cmp_lt_i32_e64 s[0:1], v7, v23
	v_mul_lo_u32 v35, v2, s75
	v_or_b32_e32 v2, 32, v3
	v_cndmask_b32_e64 v7, v157, v7, s[0:1]
	s_mul_i32 s0, s52, 0x24000
	s_mul_hi_i32 s1, s52, 0x24000
	s_add_u32 s0, s0, 0x14298900
	v_mul_u32_u24_e32 v159, 0x90, v3
	v_mul_u32_u24_e32 v23, 0xd0, v3
	v_mul_u32_u24_e32 v160, 0x90, v2
	s_addc_u32 s1, s1, 0
	v_lshlrev_b64 v[2:3], 6, v[16:17]
	s_mul_hi_i32 s16, s52, 0x120000
	s_mul_i32 s52, s52, 0x120000
	v_lshl_add_u64 v[2:3], s[0:1], 0, v[2:3]
	s_add_u32 s24, s52, 0x1309f900
	v_lshl_add_u64 v[128:129], v[20:21], 1, v[2:3]
	s_addc_u32 s25, s16, 0
	v_lshlrev_b64 v[2:3], 9, v[16:17]
	v_lshlrev_b32_e32 v123, 2, v7
	v_lshlrev_b32_e32 v32, 4, v6
	v_lshl_add_u64 v[2:3], s[24:25], 0, v[2:3]
	v_lshl_add_u64 v[6:7], v[18:19], 0, v[120:121]
	v_lshl_add_u64 v[130:131], v[6:7], 1, v[2:3]
	v_lshlrev_b64 v[2:3], 6, v[8:9]
	v_subrev_u32_e32 v28, 64, v10
	v_mov_b32_e32 v29, v117
	v_lshl_add_u64 v[2:3], s[0:1], 0, v[2:3]
	v_lshl_add_u64 v[132:133], v[28:29], 1, v[2:3]
	v_lshlrev_b64 v[2:3], 9, v[8:9]
	v_lshl_add_u64 v[2:3], s[24:25], 0, v[2:3]
	v_lshl_add_u64 v[6:7], v[120:121], 0, v[10:11]
	v_lshl_add_u64 v[134:135], v[6:7], 1, v[2:3]
	v_lshlrev_b64 v[2:3], 6, v[0:1]
	v_subrev_u32_e32 v26, 64, v4
	v_mov_b32_e32 v27, v117
	v_mul_lo_u32 v31, v0, s76
	v_lshl_add_u64 v[2:3], s[0:1], 0, v[2:3]
	v_lshlrev_b64 v[0:1], 9, v[0:1]
	v_mul_lo_u32 v33, v8, s76
	v_lshlrev_b32_e32 v12, 4, v12
	v_mul_lo_u32 v34, v16, s76
	v_lshlrev_b32_e32 v22, 4, v22
	v_mul_lo_u32 v13, v13, s75
	v_or_b32_e32 v14, v14, v30
	v_or_b32_e32 v24, v24, v30
	v_lshl_add_u64 v[136:137], v[26:27], 1, v[2:3]
	v_lshl_add_u64 v[0:1], s[24:25], 0, v[0:1]
	v_lshl_add_u64 v[2:3], v[120:121], 0, v[4:5]
	v_mov_b32_e32 v108, 0
	v_sub_u32_e32 v158, v116, v122
	v_lshl_add_u64 v[124:125], v[14:15], 0, s[42:43]
	v_lshl_add_u64 v[126:127], v[24:25], 0, s[42:43]
	v_lshl_add_u64 v[138:139], v[2:3], 1, v[0:1]
	v_mov_b32_e32 v109, 0xf149f2ca
	s_mov_b32 s0, 35
	v_add_u32_e32 v161, v31, v32
	v_add_u32_e32 v162, v33, v12
	v_add_u32_e32 v163, v34, v22
	v_add_u32_e32 v164, v30, v13
	v_add_u32_e32 v165, v30, v35
	v_add_u32_e32 v116, v116, v23
	v_mov_b32_e32 v0, 0
	v_mov_b32_e32 v1, v108
	v_mov_b32_e32 v2, v108
	v_mov_b32_e32 v3, v108
	v_mov_b32_e32 v4, v108
	v_mov_b32_e32 v5, v108
	v_mov_b32_e32 v6, v108
	v_mov_b32_e32 v7, v108
	v_mov_b32_e32 v8, v108
	v_mov_b32_e32 v9, v108
	v_mov_b32_e32 v10, v108
	v_mov_b32_e32 v11, v108
	v_mov_b32_e32 v12, v108
	v_mov_b32_e32 v13, v108
	v_mov_b32_e32 v14, v108
	v_mov_b32_e32 v15, v108
	v_mov_b32_e32 v16, 0
	v_mov_b32_e32 v17, v108
	v_mov_b32_e32 v18, v108
	v_mov_b32_e32 v19, v108
	v_mov_b32_e32 v20, v108
	v_mov_b32_e32 v21, v108
	v_mov_b32_e32 v22, v108
	v_mov_b32_e32 v23, v108
	v_mov_b32_e32 v24, v108
	v_mov_b32_e32 v25, v108
	v_mov_b32_e32 v26, v108
	v_mov_b32_e32 v27, v108
	v_mov_b32_e32 v28, v108
	v_mov_b32_e32 v29, v108
	v_mov_b32_e32 v30, v108
	v_mov_b32_e32 v31, v108
.LBB0_1684:
	s_waitcnt lgkmcnt(0)
	s_barrier
	s_waitcnt vmcnt(0)
	ds_write_b128 v161, v[224:227]
	ds_write_b128 v162, v[228:231]
	ds_write_b128 v163, v[232:235]
	ds_write_b128 v164, v[236:239] offset:13312
	ds_write_b128 v165, v[240:243] offset:13312
	s_waitcnt lgkmcnt(0)
	s_barrier
	ds_read_b128 v[32:35], v116
	ds_read_b128 v[88:91], v116 offset:32
	v_lshl_add_u64 v[100:101], s[8:9], 0, v[138:139]
	v_lshl_add_u64 v[144:145], s[8:9], 0, v[136:137]
	v_lshl_add_u64 v[102:103], s[8:9], 0, v[134:135]
	v_lshl_add_u64 v[106:107], s[8:9], 0, v[132:133]
	v_lshl_add_u64 v[104:105], s[8:9], 0, v[130:131]
	v_lshl_add_u64 v[140:141], s[8:9], 0, v[128:129]
	v_lshl_add_u64 v[142:143], s[8:9], 0, v[126:127]
	v_lshl_add_u64 v[146:147], s[8:9], 0, v[124:125]
	v_cndmask_b32_e32 v97, v145, v101, vcc
	v_cndmask_b32_e32 v96, v144, v100, vcc
	v_cndmask_b32_e64 v99, v107, v103, s[4:5]
	v_cndmask_b32_e64 v98, v106, v102, s[4:5]
	v_cndmask_b32_e64 v145, v141, v105, s[6:7]
	v_cndmask_b32_e64 v144, v140, v104, s[6:7]
	global_load_dwordx4 v[236:239], v[142:143], off
	global_load_dwordx4 v[240:243], v[146:147], off
	global_load_dwordx4 v[224:227], v[96:97], off
	global_load_dwordx4 v[228:231], v[98:99], off
	global_load_dwordx4 v[232:235], v[144:145], off
	s_waitcnt lgkmcnt(1)
	v_mfma_f32_32x32x16_bf16 v[32:47], v[32:35], v[84:87], 0
	ds_read_b128 v[48:51], v116 offset:6656
	ds_read_b128 v[92:95], v116 offset:6688
	v_mov_b32_e32 v167, v109
	v_mov_b32_e32 v166, v108
	s_waitcnt lgkmcnt(1)
	v_mfma_f32_32x32x16_bf16 v[48:63], v[48:51], v[84:87], 0
	v_add_u32_e32 v172, v122, v159
	v_add_u32_e32 v173, v122, v160
	s_add_i32 s0, s0, -1
	v_mfma_f32_32x32x16_bf16 v[32:47], v[88:91], v[80:83], v[32:47]
	ds_read_b128 v[88:91], v116 offset:64
	v_lshl_add_u64 v[124:125], v[124:125], 0, s[44:45]
	v_lshl_add_u64 v[126:127], v[126:127], 0, s[44:45]
	v_lshl_add_u64 v[128:129], v[128:129], 0, s[46:47]
	v_lshl_add_u64 v[130:131], v[130:131], 0, s[48:49]
	v_lshl_add_u64 v[132:133], v[132:133], 0, s[46:47]
	v_lshl_add_u64 v[134:135], v[134:135], 0, s[48:49]
	s_waitcnt lgkmcnt(1)
	v_mfma_f32_32x32x16_bf16 v[48:63], v[92:95], v[80:83], v[48:63]
	ds_read_b128 v[168:171], v116 offset:96
	ds_read_b128 v[92:95], v116 offset:6720
	ds_read_b128 v[96:99], v116 offset:6752
	v_lshl_add_u64 v[136:137], v[136:137], 0, s[46:47]
	v_lshl_add_u64 v[138:139], v[138:139], 0, s[48:49]
	s_cmp_lg_u32 s0, 0
	s_waitcnt lgkmcnt(3)
	v_mfma_f32_32x32x16_bf16 v[32:47], v[88:91], v[76:79], v[32:47]
	s_waitcnt lgkmcnt(1)
	v_mfma_f32_32x32x16_bf16 v[48:63], v[92:95], v[76:79], v[48:63]
	ds_read_b128 v[92:95], v116 offset:128
	ds_read_b128 v[112:115], v116 offset:160
	ds_read_b128 v[88:91], v116 offset:6784
	ds_read_b128 v[108:111], v116 offset:6816
	v_mfma_f32_32x32x16_bf16 v[32:47], v[168:171], v[72:75], v[32:47]
	v_add_u32_e32 v168, v158, v159
	v_add_u32_e32 v169, v158, v160
	s_waitcnt lgkmcnt(4)
	v_mfma_f32_32x32x16_bf16 v[48:63], v[96:99], v[72:75], v[48:63]
	s_waitcnt lgkmcnt(0)
	v_mfma_f32_32x32x16_bf16 v[32:47], v[92:95], v[68:71], v[32:47]
	v_add_u32_e32 v143, 0x3000, v172
	v_add_u32_e32 v142, 0x3000, v173
	v_add_u32_e32 v141, 0x3000, v168
	v_add_u32_e32 v140, 0x3000, v169
	v_mfma_f32_32x32x16_bf16 v[48:63], v[88:91], v[68:71], v[48:63]
	s_nop 0
	ds_read2_b64 v[144:147], v143 offset0:128 offset1:130
	v_mfma_f32_32x32x16_bf16 v[32:47], v[112:115], v[64:67], v[32:47]
	ds_read2_b64 v[112:115], v143 offset0:132 offset1:134
	ds_read2_b64 v[168:171], v142 offset0:128 offset1:130
	ds_read2_b64 v[172:175], v142 offset0:132 offset1:134
	ds_read2_b64 v[176:179], v143 offset0:136 offset1:138
	ds_read2_b64 v[180:183], v142 offset0:136 offset1:138
	ds_read2_b64 v[184:187], v141 offset0:140 offset1:142
	ds_read2_b64 v[188:191], v140 offset0:140 offset1:142
	v_mfma_f32_32x32x16_bf16 v[48:63], v[108:111], v[64:67], v[48:63]
	s_nop 3
	v_max_f32_e32 v108, v33, v33
	v_max_f32_e32 v109, v32, v32
	v_max_f32_e32 v108, v109, v108
	v_max3_f32 v108, v108, v34, v35
	v_max3_f32 v108, v108, v36, v37
	v_max3_f32 v108, v108, v38, v39
	v_max3_f32 v108, v108, v40, v41
	v_max3_f32 v108, v108, v42, v43
	v_max3_f32 v108, v108, v44, v45
	v_max3_f32 v108, v108, v46, v47
	v_max3_f32 v108, v108, v48, v49
	v_max3_f32 v108, v108, v50, v51
	v_max3_f32 v108, v108, v52, v53
	v_max3_f32 v108, v108, v54, v55
	v_max3_f32 v108, v108, v56, v57
	v_max3_f32 v108, v108, v58, v59
	v_max3_f32 v108, v108, v60, v61
	v_max3_f32 v108, v108, v62, v63
	ds_bpermute_b32 v109, v123, v108
	s_waitcnt lgkmcnt(0)
	v_max3_f32 v109, v167, v108, v109
	v_sub_f32_e32 v108, v167, v109
	v_sub_f32_e32 v32, v32, v109
	v_sub_f32_e32 v33, v33, v109
	v_sub_f32_e32 v34, v34, v109
	v_sub_f32_e32 v35, v35, v109
	v_sub_f32_e32 v36, v36, v109
	v_sub_f32_e32 v37, v37, v109
	v_sub_f32_e32 v38, v38, v109
	v_sub_f32_e32 v39, v39, v109
	v_sub_f32_e32 v110, v42, v109
	v_exp_f32_e32 v42, v108
	v_exp_f32_e32 v32, v32
	v_exp_f32_e32 v33, v33
	s_nop 0
	v_cvt_pk_bf16_f32 v244, v32, v33
	v_exp_f32_e32 v108, v34
	v_exp_f32_e32 v111, v35
	v_exp_f32_e32 v167, v36
	v_exp_f32_e32 v192, v37
	v_exp_f32_e32 v193, v38
	v_exp_f32_e32 v194, v39
	v_sub_f32_e32 v43, v43, v109
	v_sub_f32_e32 v40, v40, v109
	v_sub_f32_e32 v41, v41, v109
	v_exp_f32_e32 v43, v43
	v_exp_f32_e32 v195, v40
	v_exp_f32_e32 v196, v41
	v_add_f32_e32 v34, 0, v32
	v_bfe_u32 v39, v32, 16, 1
	v_add_f32_e32 v222, v33, v34
	v_add3_u32 v32, v32, v39, s61
	v_lshrrev_b32_e32 v32, 16, v32
	v_sub_f32_e32 v44, v44, v109
	v_sub_f32_e32 v45, v45, v109
	v_sub_f32_e32 v46, v46, v109
	v_pk_mul_f32 v[30:31], v[30:31], v[42:43] op_sel_hi:[1,0]
	v_pk_mul_f32 v[28:29], v[28:29], v[42:43] op_sel_hi:[1,0]
	v_pk_mul_f32 v[26:27], v[26:27], v[42:43] op_sel_hi:[1,0]
	v_pk_mul_f32 v[24:25], v[24:25], v[42:43] op_sel_hi:[1,0]
	v_pk_mul_f32 v[22:23], v[22:23], v[42:43] op_sel_hi:[1,0]
	v_pk_mul_f32 v[20:21], v[20:21], v[42:43] op_sel_hi:[1,0]
	v_pk_mul_f32 v[18:19], v[18:19], v[42:43] op_sel_hi:[1,0]
	v_pk_mul_f32 v[16:17], v[16:17], v[42:43] op_sel_hi:[1,0]
	v_pk_mul_f32 v[14:15], v[14:15], v[42:43] op_sel_hi:[1,0]
	v_pk_mul_f32 v[12:13], v[12:13], v[42:43] op_sel_hi:[1,0]
	v_pk_mul_f32 v[10:11], v[10:11], v[42:43] op_sel_hi:[1,0]
	v_pk_mul_f32 v[8:9], v[8:9], v[42:43] op_sel_hi:[1,0]
	v_pk_mul_f32 v[6:7], v[6:7], v[42:43] op_sel_hi:[1,0]
	v_pk_mul_f32 v[4:5], v[4:5], v[42:43] op_sel_hi:[1,0]
	v_pk_mul_f32 v[2:3], v[2:3], v[42:43] op_sel_hi:[1,0]
	v_pk_mul_f32 v[0:1], v[0:1], v[42:43] op_sel_hi:[1,0]
	v_cvt_pk_bf16_f32 v35, v193, v194
	v_cvt_pk_bf16_f32 v34, v167, v192
	v_cvt_pk_bf16_f32 v33, v108, v111
	v_mov_b32_e32 v32, v244
	v_sub_f32_e32 v47, v47, v109
	v_exp_f32_e32 v110, v110
	v_exp_f32_e32 v44, v44
	v_exp_f32_e32 v45, v45
	v_exp_f32_e32 v46, v46
	v_mfma_f32_32x32x16_bf16 v[16:31], v[144:147], v[32:35], v[16:31]
	v_exp_f32_e32 v47, v47
	v_bfe_u32 v199, v45, 16, 1
	v_bfe_u32 v202, v195, 16, 1
	v_bfe_u32 v203, v110, 16, 1
	v_bfe_u32 v204, v44, 16, 1
	v_mfma_f32_32x32x16_bf16 v[0:15], v[168:171], v[32:35], v[0:15]
	v_bfe_u32 v205, v46, 16, 1
	v_bfe_u32 v198, v47, 16, 1
	v_add3_u32 v197, v45, v199, s61
	v_add3_u32 v199, v46, v205, s61
	v_add3_u32 v200, v44, v204, s61
	v_add3_u32 v201, v110, v203, s61
	v_add3_u32 v202, v195, v202, s61
	v_add3_u32 v198, v47, v198, s61
	v_add_f32_e32 v37, v108, v222
	v_lshrrev_b32_e32 v144, 16, v199
	v_cvt_pk_bf16_f32 v35, v46, v47
	v_cvt_pk_bf16_f32 v34, v44, v45
	v_cvt_pk_bf16_f32 v33, v110, v43
	v_cvt_pk_bf16_f32 v32, v195, v196
	v_add_f32_e32 v108, v111, v37
	v_sub_f32_e32 v48, v48, v109
	v_mfma_f32_32x32x16_bf16 v[16:31], v[112:115], v[32:35], v[16:31]
	v_sub_f32_e32 v49, v49, v109
	v_sub_f32_e32 v50, v50, v109
	v_sub_f32_e32 v51, v51, v109
	v_sub_f32_e32 v52, v52, v109
	v_sub_f32_e32 v53, v53, v109
	v_sub_f32_e32 v54, v54, v109
	v_sub_f32_e32 v55, v55, v109
	v_mfma_f32_32x32x16_bf16 v[0:15], v[172:175], v[32:35], v[0:15]
	v_add_f32_e32 v32, v167, v108
	v_add_f32_e32 v32, v192, v32
	v_add_f32_e32 v32, v193, v32
	v_add_f32_e32 v32, v194, v32
	v_add_f32_e32 v32, v195, v32
	v_sub_f32_e32 v56, v56, v109
	v_exp_f32_e32 v48, v48
	v_exp_f32_e32 v49, v49
	v_exp_f32_e32 v50, v50
	v_exp_f32_e32 v51, v51
	v_exp_f32_e32 v52, v52
	v_exp_f32_e32 v53, v53
	v_exp_f32_e32 v54, v54
	v_add_f32_e32 v32, v196, v32
	v_exp_f32_e32 v55, v55
	v_exp_f32_e32 v56, v56
	v_add_f32_e32 v32, v110, v32
	v_add_f32_e32 v32, v43, v32
	v_add_f32_e32 v32, v44, v32
	v_bfe_u32 v207, v53, 16, 1
	v_bfe_u32 v208, v51, 16, 1
	v_bfe_u32 v209, v49, 16, 1
	v_bfe_u32 v210, v48, 16, 1
	v_bfe_u32 v211, v50, 16, 1
	v_bfe_u32 v212, v52, 16, 1
	v_bfe_u32 v213, v54, 16, 1
	v_add_f32_e32 v32, v45, v32
	v_bfe_u32 v206, v55, 16, 1
	v_bfe_u32 v218, v56, 16, 1
	v_add3_u32 v203, v49, v209, s61
	v_add3_u32 v204, v51, v208, s61
	v_add3_u32 v205, v53, v207, s61
	v_add3_u32 v207, v54, v213, s61
	v_add3_u32 v208, v52, v212, s61
	v_add3_u32 v209, v50, v211, s61
	v_add3_u32 v210, v48, v210, s61
	v_add_f32_e32 v32, v46, v32
	v_add3_u32 v206, v55, v206, s61
	v_lshrrev_b32_e32 v145, 16, v210
	v_lshrrev_b32_e32 v146, 16, v209
	v_lshrrev_b32_e32 v147, 16, v208
	v_lshrrev_b32_e32 v168, 16, v207
	v_add_f32_e32 v32, v47, v32
	v_sub_f32_e32 v57, v57, v109
	v_sub_f32_e32 v58, v58, v109
	v_sub_f32_e32 v59, v59, v109
	v_sub_f32_e32 v60, v60, v109
	v_sub_f32_e32 v61, v61, v109
	v_sub_f32_e32 v62, v62, v109
	v_cvt_pk_bf16_f32 v37, v54, v55
	v_cvt_pk_bf16_f32 v36, v52, v53
	v_cvt_pk_bf16_f32 v35, v50, v51
	v_cvt_pk_bf16_f32 v34, v48, v49
	v_add_f32_e32 v32, v48, v32
	v_sub_f32_e32 v63, v63, v109
	v_exp_f32_e32 v57, v57
	v_exp_f32_e32 v58, v58
	v_exp_f32_e32 v59, v59
	v_exp_f32_e32 v60, v60
	v_exp_f32_e32 v61, v61
	v_exp_f32_e32 v62, v62
	v_mfma_f32_32x32x16_bf16 v[16:31], v[176:179], v[34:37], v[16:31]
	v_add_f32_e32 v32, v49, v32
	v_exp_f32_e32 v63, v63
	v_add_f32_e32 v32, v50, v32
	v_add_f32_e32 v32, v51, v32
	v_add_f32_e32 v32, v52, v32
	v_bfe_u32 v215, v61, 16, 1
	v_bfe_u32 v216, v59, 16, 1
	v_mfma_f32_32x32x16_bf16 v[0:15], v[180:183], v[34:37], v[0:15]
	v_bfe_u32 v217, v57, 16, 1
	v_bfe_u32 v219, v58, 16, 1
	v_bfe_u32 v220, v60, 16, 1
	v_bfe_u32 v221, v62, 16, 1
	v_add_f32_e32 v32, v53, v32
	v_bfe_u32 v214, v63, 16, 1
	v_add3_u32 v211, v57, v217, s61
	v_add3_u32 v212, v59, v216, s61
	v_add3_u32 v213, v61, v215, s61
	v_add3_u32 v215, v62, v221, s61
	v_add3_u32 v216, v60, v220, s61
	v_add3_u32 v217, v58, v219, s61
	v_add_f32_e32 v32, v54, v32
	v_add3_u32 v214, v63, v214, s61
	v_add_f32_e32 v32, v55, v32
	v_cvt_pk_bf16_f32 v41, v62, v63
	v_cvt_pk_bf16_f32 v40, v60, v61
	v_cvt_pk_bf16_f32 v39, v58, v59
	v_cvt_pk_bf16_f32 v38, v56, v57
	v_add_f32_e32 v32, v56, v32
	v_add_f32_e32 v32, v57, v32
	v_mfma_f32_32x32x16_bf16 v[16:31], v[184:187], v[38:41], v[16:31]
	v_add_f32_e32 v32, v58, v32
	v_add_f32_e32 v32, v59, v32
	v_add_f32_e32 v32, v60, v32
	v_add_f32_e32 v32, v61, v32
	v_add_f32_e32 v32, v62, v32
	v_add_f32_e32 v108, v63, v32
	v_fmac_f32_e32 v108, v166, v42
	v_mfma_f32_32x32x16_bf16 v[0:15], v[188:191], v[38:41], v[0:15]
	s_cbranch_scc1 .LBB0_1684
	s_barrier
	s_waitcnt vmcnt(0)
	ds_write_b128 v161, v[224:227]
	ds_write_b128 v162, v[228:231]
	ds_write_b128 v163, v[232:235]
	ds_write_b128 v164, v[236:239] offset:13312
	ds_write_b128 v165, v[240:243] offset:13312
	s_waitcnt lgkmcnt(0)
	s_barrier
	ds_read_b128 v[32:35], v116
	ds_read_b128 v[36:39], v116 offset:32
	s_waitcnt lgkmcnt(1)
	v_mfma_f32_32x32x16_bf16 v[48:63], v[32:35], v[84:87], 0
	s_waitcnt lgkmcnt(0)
	v_mfma_f32_32x32x16_bf16 v[48:63], v[36:39], v[80:83], v[48:63]
	ds_read_b128 v[32:35], v116 offset:64
	ds_read_b128 v[36:39], v116 offset:96
	s_waitcnt lgkmcnt(1)
	v_mfma_f32_32x32x16_bf16 v[48:63], v[32:35], v[76:79], v[48:63]
	s_waitcnt lgkmcnt(0)
	v_mfma_f32_32x32x16_bf16 v[48:63], v[36:39], v[72:75], v[48:63]
	ds_read_b128 v[32:35], v116 offset:128
	ds_read_b128 v[36:39], v116 offset:160
	s_waitcnt lgkmcnt(1)
	v_mfma_f32_32x32x16_bf16 v[48:63], v[32:35], v[68:71], v[48:63]
	ds_read_b128 v[32:35], v116 offset:6656
	ds_read_b128 v[88:91], v116 offset:6688
	s_waitcnt lgkmcnt(2)
	v_mfma_f32_32x32x16_bf16 v[48:63], v[36:39], v[64:67], v[48:63]
	s_waitcnt lgkmcnt(1)
	v_mfma_f32_32x32x16_bf16 v[32:47], v[32:35], v[84:87], 0
	s_waitcnt lgkmcnt(0)
	v_mfma_f32_32x32x16_bf16 v[32:47], v[88:91], v[80:83], v[32:47]
	ds_read_b128 v[80:83], v116 offset:6720
	ds_read_b128 v[84:87], v116 offset:6752
	s_waitcnt lgkmcnt(1)
	v_mfma_f32_32x32x16_bf16 v[32:47], v[80:83], v[76:79], v[32:47]
	s_nop 3
	v_max_f32_e32 v80, v49, v49
	v_max_f32_e32 v81, v48, v48
	v_max_f32_e32 v80, v81, v80
	s_waitcnt lgkmcnt(0)
	v_mfma_f32_32x32x16_bf16 v[32:47], v[84:87], v[72:75], v[32:47]
	ds_read_b128 v[72:75], v116 offset:6784
	ds_read_b128 v[76:79], v116 offset:6816
	s_waitcnt lgkmcnt(1)
	v_mfma_f32_32x32x16_bf16 v[32:47], v[72:75], v[68:71], v[32:47]
	v_max3_f32 v68, v80, v50, v51
	v_max3_f32 v68, v68, v52, v53
	v_max3_f32 v68, v68, v54, v55
	v_max3_f32 v68, v68, v56, v57
	v_max3_f32 v68, v68, v58, v59
	v_max3_f32 v68, v68, v60, v61
	v_max3_f32 v68, v68, v62, v63
	s_waitcnt lgkmcnt(0)
	v_mfma_f32_32x32x16_bf16 v[32:47], v[76:79], v[64:67], v[32:47]
	s_nop 11
	v_max3_f32 v64, v68, v32, v33
	v_max3_f32 v64, v64, v34, v35
	v_max3_f32 v64, v64, v36, v37
	v_max3_f32 v64, v64, v38, v39
	v_max3_f32 v64, v64, v40, v41
	v_max3_f32 v64, v64, v42, v43
	v_max3_f32 v64, v64, v44, v45
	v_max3_f32 v64, v64, v46, v47
	ds_bpermute_b32 v65, v123, v64
	s_waitcnt lgkmcnt(0)
	v_max3_f32 v65, v109, v64, v65
	v_sub_f32_e32 v32, v32, v65
	v_exp_f32_e32 v66, v32
	v_sub_f32_e32 v32, v33, v65
	v_exp_f32_e32 v67, v32
	v_sub_f32_e32 v32, v34, v65
	v_exp_f32_e32 v68, v32
	v_sub_f32_e32 v32, v35, v65
	v_exp_f32_e32 v69, v32
	v_sub_f32_e32 v32, v36, v65
	v_exp_f32_e32 v70, v32
	v_sub_f32_e32 v32, v37, v65
	v_exp_f32_e32 v71, v32
	v_sub_f32_e32 v32, v38, v65
	v_exp_f32_e32 v72, v32
	v_sub_f32_e32 v32, v39, v65
	v_exp_f32_e32 v73, v32
	v_sub_f32_e32 v32, v40, v65
	v_exp_f32_e32 v74, v32
	v_sub_f32_e32 v32, v41, v65
	v_exp_f32_e32 v75, v32
	v_sub_f32_e32 v32, v42, v65
	v_sub_f32_e32 v48, v48, v65
	v_exp_f32_e32 v76, v32
	v_sub_f32_e32 v32, v43, v65
	v_exp_f32_e32 v48, v48
	v_sub_f32_e32 v49, v49, v65
	v_exp_f32_e32 v77, v32
	v_sub_f32_e32 v32, v44, v65
	v_exp_f32_e32 v49, v49
	v_sub_f32_e32 v50, v50, v65
	v_sub_f32_e32 v55, v55, v65
	v_exp_f32_e32 v78, v32
	v_sub_f32_e32 v32, v45, v65
	v_exp_f32_e32 v50, v50
	v_sub_f32_e32 v51, v51, v65
	v_sub_f32_e32 v53, v53, v65
	v_exp_f32_e32 v55, v55
	v_exp_f32_e32 v79, v32
	v_sub_f32_e32 v32, v46, v65
	v_exp_f32_e32 v51, v51
	v_sub_f32_e32 v52, v52, v65
	v_exp_f32_e32 v53, v53
	v_sub_f32_e32 v54, v54, v65
	v_exp_f32_e32 v80, v32
	v_sub_f32_e32 v32, v47, v65
	v_sub_f32_e32 v64, v109, v65
	v_exp_f32_e32 v52, v52
	v_exp_f32_e32 v54, v54
	v_sub_f32_e32 v56, v56, v65
	v_sub_f32_e32 v57, v57, v65
	v_sub_f32_e32 v58, v58, v65
	v_sub_f32_e32 v59, v59, v65
	v_sub_f32_e32 v60, v60, v65
	v_sub_f32_e32 v61, v61, v65
	v_sub_f32_e32 v62, v62, v65
	v_sub_f32_e32 v63, v63, v65
	v_exp_f32_e32 v65, v32
	v_add_f32_e32 v32, 0, v48
	v_add_f32_e32 v32, v49, v32
	v_add_f32_e32 v44, v50, v32
	ds_read2_b64 v[32:35], v143 offset0:128 offset1:130
	v_exp_f32_e32 v64, v64
	v_cvt_pk_bf16_f32 v39, v54, v55
	v_cvt_pk_bf16_f32 v38, v52, v53
	v_cvt_pk_bf16_f32 v37, v50, v51
	v_cvt_pk_bf16_f32 v36, v48, v49
	ds_read2_b64 v[40:43], v142 offset0:128 offset1:130
	v_pk_mul_f32 v[30:31], v[30:31], v[64:65] op_sel_hi:[1,0]
	v_pk_mul_f32 v[28:29], v[28:29], v[64:65] op_sel_hi:[1,0]
	v_pk_mul_f32 v[26:27], v[26:27], v[64:65] op_sel_hi:[1,0]
	v_pk_mul_f32 v[24:25], v[24:25], v[64:65] op_sel_hi:[1,0]
	v_pk_mul_f32 v[22:23], v[22:23], v[64:65] op_sel_hi:[1,0]
	v_pk_mul_f32 v[20:21], v[20:21], v[64:65] op_sel_hi:[1,0]
	v_pk_mul_f32 v[18:19], v[18:19], v[64:65] op_sel_hi:[1,0]
	v_pk_mul_f32 v[16:17], v[16:17], v[64:65] op_sel_hi:[1,0]
	v_exp_f32_e32 v57, v57
	v_exp_f32_e32 v59, v59
	s_waitcnt lgkmcnt(1)
	v_mfma_f32_32x32x16_bf16 v[16:31], v[32:35], v[36:39], v[16:31]
	v_add_f32_e32 v32, v51, v44
	v_exp_f32_e32 v56, v56
	v_exp_f32_e32 v58, v58
	v_exp_f32_e32 v60, v60
	v_exp_f32_e32 v62, v62
	v_add_f32_e32 v32, v52, v32
	v_exp_f32_e32 v61, v61
	v_exp_f32_e32 v63, v63
	v_add_f32_e32 v32, v53, v32
	v_pk_mul_f32 v[14:15], v[14:15], v[64:65] op_sel_hi:[1,0]
	v_pk_mul_f32 v[12:13], v[12:13], v[64:65] op_sel_hi:[1,0]
	v_pk_mul_f32 v[10:11], v[10:11], v[64:65] op_sel_hi:[1,0]
	v_pk_mul_f32 v[8:9], v[8:9], v[64:65] op_sel_hi:[1,0]
	v_pk_mul_f32 v[6:7], v[6:7], v[64:65] op_sel_hi:[1,0]
	v_pk_mul_f32 v[4:5], v[4:5], v[64:65] op_sel_hi:[1,0]
	v_pk_mul_f32 v[2:3], v[2:3], v[64:65] op_sel_hi:[1,0]
	v_pk_mul_f32 v[0:1], v[0:1], v[64:65] op_sel_hi:[1,0]
	v_add_f32_e32 v32, v54, v32
	v_add_f32_e32 v48, v55, v32
	s_waitcnt lgkmcnt(0)
	v_mfma_f32_32x32x16_bf16 v[0:15], v[40:43], v[36:39], v[0:15]
	ds_read2_b64 v[32:35], v143 offset0:132 offset1:134
	ds_read2_b64 v[44:47], v142 offset0:132 offset1:134
	v_add_f32_e32 v40, v56, v48
	v_bfe_u32 v38, v56, 16, 1
	v_bfe_u32 v39, v58, 16, 1
	v_bfe_u32 v48, v62, 16, 1
	v_add3_u32 v48, v62, v48, s61
	v_add3_u32 v39, v58, v39, s61
	v_add3_u32 v38, v56, v38, s61
	v_lshrrev_b32_e32 v49, 16, v38
	v_lshrrev_b32_e32 v50, 16, v39
	v_cvt_pk_bf16_f32 v39, v62, v63
	v_cvt_pk_bf16_f32 v38, v60, v61
	v_cvt_pk_bf16_f32 v37, v58, v59
	v_cvt_pk_bf16_f32 v36, v56, v57
	s_waitcnt lgkmcnt(1)
	s_nop 0
	v_mfma_f32_32x32x16_bf16 v[16:31], v[32:35], v[36:39], v[16:31]
	v_add_f32_e32 v32, v57, v40
	v_add_f32_e32 v32, v58, v32
	v_add_f32_e32 v32, v59, v32
	v_add_f32_e32 v32, v60, v32
	v_add_f32_e32 v32, v61, v32
	v_add_f32_e32 v32, v62, v32
	v_add_f32_e32 v32, v63, v32
	s_waitcnt lgkmcnt(0)
	v_mfma_f32_32x32x16_bf16 v[0:15], v[44:47], v[36:39], v[0:15]
	v_add_f32_e32 v44, v66, v32
	ds_read2_b64 v[32:35], v143 offset0:136 offset1:138
	v_cvt_pk_bf16_f32 v39, v72, v73
	v_cvt_pk_bf16_f32 v38, v70, v71
	v_cvt_pk_bf16_f32 v37, v68, v69
	v_cvt_pk_bf16_f32 v36, v66, v67
	ds_read2_b64 v[40:43], v142 offset0:136 offset1:138
	s_waitcnt lgkmcnt(1)
	v_mfma_f32_32x32x16_bf16 v[16:31], v[32:35], v[36:39], v[16:31]
	v_add_f32_e32 v32, v67, v44
	v_add_f32_e32 v32, v68, v32
	v_add_f32_e32 v32, v69, v32
	v_add_f32_e32 v32, v70, v32
	v_add_f32_e32 v32, v71, v32
	v_add_f32_e32 v32, v72, v32
	v_add_f32_e32 v32, v73, v32
	v_add_f32_e32 v32, v74, v32
	v_add_f32_e32 v32, v75, v32
	v_add_f32_e32 v32, v76, v32
	v_add_f32_e32 v32, v77, v32
	v_add_f32_e32 v32, v78, v32
	v_add_f32_e32 v32, v79, v32
	v_add_f32_e32 v32, v80, v32
	s_waitcnt lgkmcnt(0)
	v_mfma_f32_32x32x16_bf16 v[0:15], v[40:43], v[36:39], v[0:15]
	v_add_f32_e32 v40, v65, v32
	v_bfe_u32 v32, v74, 16, 1
	v_bfe_u32 v33, v76, 16, 1
	v_add3_u32 v33, v76, v33, s61
	v_add3_u32 v32, v74, v32, s61
	v_lshrrev_b32_e32 v43, 16, v32
	v_lshrrev_b32_e32 v44, 16, v33
	ds_read2_b64 v[32:35], v141 offset0:140 offset1:142
	v_fmac_f32_e32 v40, v108, v64
	v_cvt_pk_bf16_f32 v39, v80, v65
	ds_bpermute_b32 v41, v123, v40
	v_cvt_pk_bf16_f32 v38, v78, v79
	v_cvt_pk_bf16_f32 v37, v76, v77
	v_cvt_pk_bf16_f32 v36, v74, v75
	v_mov_b32_e32 v123, v117
	s_waitcnt lgkmcnt(0)
	v_add_f32_e32 v40, v40, v41
	v_mfma_f32_32x32x16_bf16 v[16:31], v[32:35], v[36:39], v[16:31]
	ds_read2_b64 v[32:35], v140 offset0:140 offset1:142
	v_div_scale_f32 v41, s[0:1], v40, v40, 1.0
	v_rcp_f32_e32 v42, v41
	s_waitcnt lgkmcnt(0)
	v_mfma_f32_32x32x16_bf16 v[0:15], v[32:35], v[36:39], v[0:15]
	v_fma_f32 v32, -v41, v42, 1.0
	v_fmac_f32_e32 v42, v32, v42
	v_div_scale_f32 v32, vcc, 1.0, v40, 1.0
	v_mul_f32_e32 v33, v32, v42
	v_fma_f32 v34, -v41, v33, v32
	v_fmac_f32_e32 v33, v34, v42
	v_fma_f32 v32, -v41, v33, v32
	v_div_fmas_f32 v32, v32, v42, v33
	v_div_fixup_f32 v32, v32, v40, 1.0
	v_mov_b32_e32 v38, v16
	v_mov_b32_e32 v39, v18
	v_mov_b32_e32 v18, v17
	v_lshlrev_b64 v[34:35], 11, v[118:119]
	v_pk_mul_f32 v[38:39], v[38:39], v[32:33] op_sel_hi:[1,0]
	v_pk_mul_f32 v[16:17], v[18:19], v[32:33] op_sel_hi:[1,0]
	v_lshl_add_u64 v[34:35], s[8:9], 0, v[34:35]
	v_and_b32_sdwa v19, v38, v155 dst_sel:DWORD dst_unused:UNUSED_PAD src0_sel:WORD_1 src1_sel:DWORD
	v_and_b32_sdwa v33, v17, v155 dst_sel:DWORD dst_unused:UNUSED_PAD src0_sel:WORD_1 src1_sel:DWORD
	v_lshl_add_u64 v[34:35], v[120:121], 1, v[34:35]
	v_and_b32_sdwa v18, v39, v155 dst_sel:DWORD dst_unused:UNUSED_PAD src0_sel:WORD_1 src1_sel:DWORD
	v_add3_u32 v19, v38, v19, s61
	v_and_b32_sdwa v38, v16, v155 dst_sel:DWORD dst_unused:UNUSED_PAD src0_sel:WORD_1 src1_sel:DWORD
	v_add3_u32 v17, v17, v33, s61
	v_lshl_add_u64 v[34:35], v[34:35], 0, v[122:123]
	v_add3_u32 v18, v39, v18, s61
	v_add3_u32 v16, v16, v38, s61
	v_and_b32_e32 v17, 0xffff0000, v17
	v_and_b32_e32 v16, 0xffff0000, v16
	v_or_b32_sdwa v17, v17, v18 dst_sel:DWORD dst_unused:UNUSED_PAD src0_sel:DWORD src1_sel:WORD_1
	v_add_co_u32_e32 v18, vcc, s63, v34
	v_or_b32_sdwa v16, v16, v19 dst_sel:DWORD dst_unused:UNUSED_PAD src0_sel:DWORD src1_sel:WORD_1
	s_nop 0
	v_addc_co_u32_e32 v19, vcc, 0, v35, vcc
	global_store_dwordx2 v[18:19], v[16:17], off offset:3840
	v_mov_b32_e32 v16, v20
	v_mov_b32_e32 v17, v22
	v_pk_mul_f32 v[16:17], v[16:17], v[32:33] op_sel_hi:[1,0]
	v_mov_b32_e32 v22, v21
	v_pk_mul_f32 v[18:19], v[22:23], v[32:33] op_sel_hi:[1,0]
	v_and_b32_sdwa v20, v17, v155 dst_sel:DWORD dst_unused:UNUSED_PAD src0_sel:WORD_1 src1_sel:DWORD
	v_and_b32_sdwa v21, v16, v155 dst_sel:DWORD dst_unused:UNUSED_PAD src0_sel:WORD_1 src1_sel:DWORD
	v_add3_u32 v16, v16, v21, s61
	v_add3_u32 v17, v17, v20, s61
	v_and_b32_sdwa v20, v19, v155 dst_sel:DWORD dst_unused:UNUSED_PAD src0_sel:WORD_1 src1_sel:DWORD
	v_and_b32_sdwa v21, v18, v155 dst_sel:DWORD dst_unused:UNUSED_PAD src0_sel:WORD_1 src1_sel:DWORD
	v_add3_u32 v19, v19, v20, s61
	v_add3_u32 v18, v18, v21, s61
	v_and_b32_e32 v19, 0xffff0000, v19
	v_and_b32_e32 v18, 0xffff0000, v18
	v_lshl_add_u64 v[36:37], v[34:35], 0, s[50:51]
	v_or_b32_sdwa v17, v19, v17 dst_sel:DWORD dst_unused:UNUSED_PAD src0_sel:DWORD src1_sel:WORD_1
	v_or_b32_sdwa v16, v18, v16 dst_sel:DWORD dst_unused:UNUSED_PAD src0_sel:DWORD src1_sel:WORD_1
	global_store_dwordx2 v[36:37], v[16:17], off offset:16
	v_mov_b32_e32 v16, v24
	v_mov_b32_e32 v17, v26
	v_pk_mul_f32 v[16:17], v[16:17], v[32:33] op_sel_hi:[1,0]
	v_mov_b32_e32 v26, v25
	v_pk_mul_f32 v[18:19], v[26:27], v[32:33] op_sel_hi:[1,0]
	v_and_b32_sdwa v20, v17, v155 dst_sel:DWORD dst_unused:UNUSED_PAD src0_sel:WORD_1 src1_sel:DWORD
	v_and_b32_sdwa v21, v16, v155 dst_sel:DWORD dst_unused:UNUSED_PAD src0_sel:WORD_1 src1_sel:DWORD
	v_add3_u32 v16, v16, v21, s61
	v_add3_u32 v17, v17, v20, s61
	v_and_b32_sdwa v20, v19, v155 dst_sel:DWORD dst_unused:UNUSED_PAD src0_sel:WORD_1 src1_sel:DWORD
	v_and_b32_sdwa v21, v18, v155 dst_sel:DWORD dst_unused:UNUSED_PAD src0_sel:WORD_1 src1_sel:DWORD
	v_add3_u32 v19, v19, v20, s61
	v_add3_u32 v18, v18, v21, s61
	v_and_b32_e32 v19, 0xffff0000, v19
	v_and_b32_e32 v18, 0xffff0000, v18
	v_or_b32_sdwa v17, v19, v17 dst_sel:DWORD dst_unused:UNUSED_PAD src0_sel:DWORD src1_sel:WORD_1
	v_or_b32_sdwa v16, v18, v16 dst_sel:DWORD dst_unused:UNUSED_PAD src0_sel:DWORD src1_sel:WORD_1
	global_store_dwordx2 v[36:37], v[16:17], off offset:32
	v_mov_b32_e32 v16, v28
	v_mov_b32_e32 v17, v30
	v_pk_mul_f32 v[16:17], v[16:17], v[32:33] op_sel_hi:[1,0]
	v_mov_b32_e32 v30, v29
	v_pk_mul_f32 v[18:19], v[30:31], v[32:33] op_sel_hi:[1,0]
	v_and_b32_sdwa v20, v17, v155 dst_sel:DWORD dst_unused:UNUSED_PAD src0_sel:WORD_1 src1_sel:DWORD
	v_and_b32_sdwa v21, v16, v155 dst_sel:DWORD dst_unused:UNUSED_PAD src0_sel:WORD_1 src1_sel:DWORD
	v_add3_u32 v16, v16, v21, s61
	v_add3_u32 v17, v17, v20, s61
	v_and_b32_sdwa v20, v19, v155 dst_sel:DWORD dst_unused:UNUSED_PAD src0_sel:WORD_1 src1_sel:DWORD
	v_and_b32_sdwa v21, v18, v155 dst_sel:DWORD dst_unused:UNUSED_PAD src0_sel:WORD_1 src1_sel:DWORD
	v_add3_u32 v19, v19, v20, s61
	v_add3_u32 v18, v18, v21, s61
	v_and_b32_e32 v19, 0xffff0000, v19
	v_and_b32_e32 v18, 0xffff0000, v18
	v_or_b32_sdwa v17, v19, v17 dst_sel:DWORD dst_unused:UNUSED_PAD src0_sel:DWORD src1_sel:WORD_1
	v_or_b32_sdwa v16, v18, v16 dst_sel:DWORD dst_unused:UNUSED_PAD src0_sel:DWORD src1_sel:WORD_1
	global_store_dwordx2 v[36:37], v[16:17], off offset:48
	v_mov_b32_e32 v16, v0
	v_mov_b32_e32 v17, v2
	v_pk_mul_f32 v[16:17], v[16:17], v[32:33] op_sel_hi:[1,0]
	v_mov_b32_e32 v2, v1
	v_pk_mul_f32 v[0:1], v[2:3], v[32:33] op_sel_hi:[1,0]
	v_and_b32_sdwa v2, v17, v155 dst_sel:DWORD dst_unused:UNUSED_PAD src0_sel:WORD_1 src1_sel:DWORD
	v_and_b32_sdwa v3, v16, v155 dst_sel:DWORD dst_unused:UNUSED_PAD src0_sel:WORD_1 src1_sel:DWORD
	v_add3_u32 v3, v16, v3, s61
	v_add3_u32 v2, v17, v2, s61
	v_and_b32_sdwa v16, v1, v155 dst_sel:DWORD dst_unused:UNUSED_PAD src0_sel:WORD_1 src1_sel:DWORD
	v_and_b32_sdwa v17, v0, v155 dst_sel:DWORD dst_unused:UNUSED_PAD src0_sel:WORD_1 src1_sel:DWORD
	v_add3_u32 v1, v1, v16, s61
	v_add3_u32 v0, v0, v17, s61
	v_and_b32_e32 v1, 0xffff0000, v1
	v_and_b32_e32 v0, 0xffff0000, v0
	v_or_b32_sdwa v1, v1, v2 dst_sel:DWORD dst_unused:UNUSED_PAD src0_sel:DWORD src1_sel:WORD_1
	v_or_b32_sdwa v0, v0, v3 dst_sel:DWORD dst_unused:UNUSED_PAD src0_sel:DWORD src1_sel:WORD_1
	global_store_dwordx2 v[36:37], v[0:1], off offset:64
	v_mov_b32_e32 v0, v4
	v_mov_b32_e32 v1, v6
	v_pk_mul_f32 v[0:1], v[0:1], v[32:33] op_sel_hi:[1,0]
	v_mov_b32_e32 v6, v5
	v_pk_mul_f32 v[2:3], v[6:7], v[32:33] op_sel_hi:[1,0]
	v_and_b32_sdwa v4, v1, v155 dst_sel:DWORD dst_unused:UNUSED_PAD src0_sel:WORD_1 src1_sel:DWORD
	v_and_b32_sdwa v5, v0, v155 dst_sel:DWORD dst_unused:UNUSED_PAD src0_sel:WORD_1 src1_sel:DWORD
	v_add3_u32 v0, v0, v5, s61
	v_add3_u32 v1, v1, v4, s61
	v_and_b32_sdwa v4, v3, v155 dst_sel:DWORD dst_unused:UNUSED_PAD src0_sel:WORD_1 src1_sel:DWORD
	v_and_b32_sdwa v5, v2, v155 dst_sel:DWORD dst_unused:UNUSED_PAD src0_sel:WORD_1 src1_sel:DWORD
	v_add3_u32 v3, v3, v4, s61
	v_add3_u32 v2, v2, v5, s61
	v_and_b32_e32 v3, 0xffff0000, v3
	v_and_b32_e32 v2, 0xffff0000, v2
	v_or_b32_sdwa v1, v3, v1 dst_sel:DWORD dst_unused:UNUSED_PAD src0_sel:DWORD src1_sel:WORD_1
	v_or_b32_sdwa v0, v2, v0 dst_sel:DWORD dst_unused:UNUSED_PAD src0_sel:DWORD src1_sel:WORD_1
	global_store_dwordx2 v[36:37], v[0:1], off offset:80
	v_mov_b32_e32 v0, v8
	v_mov_b32_e32 v1, v10
	v_pk_mul_f32 v[0:1], v[0:1], v[32:33] op_sel_hi:[1,0]
	v_mov_b32_e32 v10, v9
	v_pk_mul_f32 v[2:3], v[10:11], v[32:33] op_sel_hi:[1,0]
	v_and_b32_sdwa v4, v1, v155 dst_sel:DWORD dst_unused:UNUSED_PAD src0_sel:WORD_1 src1_sel:DWORD
	v_and_b32_sdwa v5, v0, v155 dst_sel:DWORD dst_unused:UNUSED_PAD src0_sel:WORD_1 src1_sel:DWORD
	v_add3_u32 v0, v0, v5, s61
	v_add3_u32 v1, v1, v4, s61
	v_and_b32_sdwa v4, v3, v155 dst_sel:DWORD dst_unused:UNUSED_PAD src0_sel:WORD_1 src1_sel:DWORD
	v_and_b32_sdwa v5, v2, v155 dst_sel:DWORD dst_unused:UNUSED_PAD src0_sel:WORD_1 src1_sel:DWORD
	v_add3_u32 v3, v3, v4, s61
	v_add3_u32 v2, v2, v5, s61
	v_and_b32_e32 v3, 0xffff0000, v3
	v_and_b32_e32 v2, 0xffff0000, v2
	v_or_b32_sdwa v1, v3, v1 dst_sel:DWORD dst_unused:UNUSED_PAD src0_sel:DWORD src1_sel:WORD_1
	v_or_b32_sdwa v0, v2, v0 dst_sel:DWORD dst_unused:UNUSED_PAD src0_sel:DWORD src1_sel:WORD_1
	global_store_dwordx2 v[36:37], v[0:1], off offset:96
	v_mov_b32_e32 v0, v12
	v_mov_b32_e32 v1, v14
	v_pk_mul_f32 v[0:1], v[0:1], v[32:33] op_sel_hi:[1,0]
	v_mov_b32_e32 v14, v13
	v_pk_mul_f32 v[2:3], v[14:15], v[32:33] op_sel_hi:[1,0]
	v_and_b32_sdwa v4, v1, v155 dst_sel:DWORD dst_unused:UNUSED_PAD src0_sel:WORD_1 src1_sel:DWORD
	v_and_b32_sdwa v5, v0, v155 dst_sel:DWORD dst_unused:UNUSED_PAD src0_sel:WORD_1 src1_sel:DWORD
	v_add3_u32 v0, v0, v5, s61
	v_add3_u32 v1, v1, v4, s61
	v_and_b32_sdwa v4, v3, v155 dst_sel:DWORD dst_unused:UNUSED_PAD src0_sel:WORD_1 src1_sel:DWORD
	v_and_b32_sdwa v5, v2, v155 dst_sel:DWORD dst_unused:UNUSED_PAD src0_sel:WORD_1 src1_sel:DWORD
	v_add3_u32 v3, v3, v4, s61
	v_add3_u32 v2, v2, v5, s61
	v_and_b32_e32 v3, 0xffff0000, v3
	v_and_b32_e32 v2, 0xffff0000, v2
	v_or_b32_sdwa v1, v3, v1 dst_sel:DWORD dst_unused:UNUSED_PAD src0_sel:DWORD src1_sel:WORD_1
	v_or_b32_sdwa v0, v2, v0 dst_sel:DWORD dst_unused:UNUSED_PAD src0_sel:DWORD src1_sel:WORD_1
	global_store_dwordx2 v[36:37], v[0:1], off offset:112
	s_branch .LBB0_1562
